# mix3: LRU pass-3 prefix/main loops and GLA-C stage-2 GST/PV loops: loads of an iteration issued together with counted waits
# speedup vs baseline: 1.1606x; 1.0116x over previous
.LBB0_245:
	v_add_co_u32_e32 v34, vcc, 0xffffd000, v8
	v_add_u32_e32 v37, s2, v6
	s_nop 0
	v_addc_co_u32_e32 v35, vcc, -1, v9, vcc
	global_load_dwordx4 v[38:41], v[34:35], off offset:-8
	v_add_co_u32_e32 v34, vcc, 0xffffe000, v8
	s_nop 1
	v_addc_co_u32_e32 v35, vcc, -1, v9, vcc
	global_load_dwordx4 v[42:45], v[34:35], off offset:-8
	v_add_co_u32_e32 v46, vcc, 0xfffff000, v8
	s_nop 1
	v_addc_co_u32_e32 v47, vcc, -1, v9, vcc
	global_load_dwordx4 v[48:51], v[46:47], off offset:-8
	global_load_dwordx4 v[52:55], v[8:9], off offset:-8
	v_add_u32_e32 v46, 2, v37
	v_ashrrev_i32_e32 v47, 31, v46
	v_lshlrev_b64 v[46:47], 13, v[46:47]
	v_lshl_add_u64 v[46:47], s[70:71], 0, v[46:47]
	v_lshl_add_u64 v[56:57], v[46:47], 0, v[96:97]
	global_load_dwordx4 v[58:61], v[56:57], off
	v_add_co_u32_e32 v56, vcc, s7, v56
	s_nop 1
	v_addc_co_u32_e32 v57, vcc, 0, v57, vcc
	global_load_dwordx4 v[102:105], v[56:57], off
	v_add_u32_e32 v46, 3, v37
	v_ashrrev_i32_e32 v47, 31, v46
	v_lshlrev_b64 v[46:47], 13, v[46:47]
	v_lshl_add_u64 v[46:47], s[70:71], 0, v[46:47]
	v_lshl_add_u64 v[56:57], v[46:47], 0, v[96:97]
	global_load_dwordx4 v[106:109], v[56:57], off
	v_add_co_u32_e32 v56, vcc, s7, v56
	s_nop 1
	v_addc_co_u32_e32 v57, vcc, 0, v57, vcc
	global_load_dwordx4 v[210:213], v[56:57], off
	v_add_u32_e32 v46, 4, v37
	v_ashrrev_i32_e32 v47, 31, v46
	v_lshlrev_b64 v[46:47], 13, v[46:47]
	v_lshl_add_u64 v[46:47], s[70:71], 0, v[46:47]
	v_lshl_add_u64 v[56:57], v[46:47], 0, v[96:97]
	global_load_dwordx4 v[214:217], v[56:57], off
	v_add_co_u32_e32 v56, vcc, s7, v56
	s_nop 1
	v_addc_co_u32_e32 v57, vcc, 0, v57, vcc
	global_load_dwordx4 v[218:221], v[56:57], off
	v_add_u32_e32 v46, 5, v37
	v_ashrrev_i32_e32 v47, 31, v46
	v_lshlrev_b64 v[46:47], 13, v[46:47]
	v_lshl_add_u64 v[46:47], s[70:71], 0, v[46:47]
	v_lshl_add_u64 v[56:57], v[46:47], 0, v[96:97]
	global_load_dwordx4 v[222:225], v[56:57], off
	v_add_co_u32_e32 v56, vcc, s7, v56
	s_nop 1
	v_addc_co_u32_e32 v57, vcc, 0, v57, vcc
	global_load_dwordx4 v[226:229], v[56:57], off
	v_add_u32_e32 v46, 6, v37
	v_ashrrev_i32_e32 v47, 31, v46
	v_lshlrev_b64 v[46:47], 13, v[46:47]
	v_lshl_add_u64 v[46:47], s[70:71], 0, v[46:47]
	v_lshl_add_u64 v[46:47], v[46:47], 0, v[96:97]
	global_load_dwordx4 v[230:233], v[46:47], off
	v_add_co_u32_e32 v46, vcc, s7, v46
	s_nop 1
	v_addc_co_u32_e32 v47, vcc, 0, v47, vcc
	global_load_dwordx4 v[234:237], v[46:47], off
	v_add_u32_e32 v62, 7, v37
	v_ashrrev_i32_e32 v63, 31, v62
	v_lshlrev_b64 v[62:63], 13, v[62:63]
	v_lshl_add_u64 v[62:63], s[70:71], 0, v[62:63]
	v_lshl_add_u64 v[62:63], v[62:63], 0, v[96:97]
	global_load_dwordx4 v[238:241], v[62:63], off
	v_add_co_u32_e32 v62, vcc, s7, v62
	s_nop 1
	v_addc_co_u32_e32 v63, vcc, 0, v63, vcc
	global_load_dwordx4 v[242:245], v[62:63], off
	v_add_co_u32_e32 v10, vcc, 0xffffd000, v8
	v_add_u32_e32 v7, s2, v6
	s_nop 0
	v_addc_co_u32_e32 v11, vcc, -1, v9, vcc
	s_waitcnt vmcnt(15)
	v_mov_b32_e32 v14, v38
	v_mov_b32_e32 v15, v39
	v_mov_b32_e32 v16, v40
	v_mov_b32_e32 v17, v41
	v_add_co_u32_e32 v10, vcc, 0xffffe000, v8
	s_add_i32 s2, s2, 8
	s_nop 0
	v_addc_co_u32_e32 v11, vcc, -1, v9, vcc
	s_waitcnt vmcnt(14)
	v_mov_b32_e32 v18, v42
	v_mov_b32_e32 v19, v43
	v_mov_b32_e32 v20, v44
	v_mov_b32_e32 v21, v45
	s_nop 0
	v_pk_fma_f32 v[18:19], v[0:1], v[14:15], v[18:19]
	v_add_co_u32_e32 v0, vcc, 0xfffff000, v8
	v_pk_fma_f32 v[10:11], v[2:3], v[16:17], v[20:21]
	s_nop 0
	v_addc_co_u32_e32 v1, vcc, -1, v9, vcc
	s_waitcnt vmcnt(13)
	v_mov_b32_e32 v0, v48
	v_mov_b32_e32 v1, v49
	v_mov_b32_e32 v2, v50
	v_mov_b32_e32 v3, v51
	s_nop 0
	s_waitcnt vmcnt(12)
	v_mov_b32_e32 v14, v52
	v_mov_b32_e32 v15, v53
	v_mov_b32_e32 v16, v54
	v_mov_b32_e32 v17, v55
	v_lshl_add_u64 v[8:9], v[8:9], 0, s[8:9]
	s_nop 0
	v_pk_fma_f32 v[18:19], v[18:19], v[0:1], v[14:15]
	v_add_u32_e32 v0, 2, v7
	v_ashrrev_i32_e32 v1, 31, v0
	v_lshlrev_b64 v[0:1], 13, v[0:1]
	v_lshl_add_u64 v[0:1], s[70:71], 0, v[0:1]
	v_lshl_add_u64 v[14:15], v[0:1], 0, v[96:97]
	v_pk_fma_f32 v[10:11], v[10:11], v[2:3], v[16:17]
	s_waitcnt vmcnt(11)
	v_mov_b32_e32 v0, v58
	v_mov_b32_e32 v1, v59
	v_mov_b32_e32 v2, v60
	v_mov_b32_e32 v3, v61
	v_add_co_u32_e32 v14, vcc, s7, v14
	s_nop 1
	v_addc_co_u32_e32 v15, vcc, 0, v15, vcc
	s_waitcnt vmcnt(10)
	v_mov_b32_e32 v14, v102
	v_mov_b32_e32 v15, v103
	v_mov_b32_e32 v16, v104
	v_mov_b32_e32 v17, v105
	s_nop 0
	v_pk_fma_f32 v[18:19], v[18:19], v[0:1], v[14:15]
	v_add_u32_e32 v0, 3, v7
	v_ashrrev_i32_e32 v1, 31, v0
	v_lshlrev_b64 v[0:1], 13, v[0:1]
	v_lshl_add_u64 v[0:1], s[70:71], 0, v[0:1]
	v_lshl_add_u64 v[14:15], v[0:1], 0, v[96:97]
	v_pk_fma_f32 v[10:11], v[10:11], v[2:3], v[16:17]
	s_waitcnt vmcnt(9)
	v_mov_b32_e32 v0, v106
	v_mov_b32_e32 v1, v107
	v_mov_b32_e32 v2, v108
	v_mov_b32_e32 v3, v109
	v_add_co_u32_e32 v14, vcc, s7, v14
	s_nop 1
	v_addc_co_u32_e32 v15, vcc, 0, v15, vcc
	s_waitcnt vmcnt(8)
	v_mov_b32_e32 v14, v210
	v_mov_b32_e32 v15, v211
	v_mov_b32_e32 v16, v212
	v_mov_b32_e32 v17, v213
	s_nop 0
	v_pk_fma_f32 v[18:19], v[18:19], v[0:1], v[14:15]
	v_add_u32_e32 v0, 4, v7
	v_ashrrev_i32_e32 v1, 31, v0
	v_lshlrev_b64 v[0:1], 13, v[0:1]
	v_lshl_add_u64 v[0:1], s[70:71], 0, v[0:1]
	v_lshl_add_u64 v[14:15], v[0:1], 0, v[96:97]
	v_pk_fma_f32 v[10:11], v[10:11], v[2:3], v[16:17]
	s_waitcnt vmcnt(7)
	v_mov_b32_e32 v0, v214
	v_mov_b32_e32 v1, v215
	v_mov_b32_e32 v2, v216
	v_mov_b32_e32 v3, v217
	v_add_co_u32_e32 v14, vcc, s7, v14
	s_nop 1
	v_addc_co_u32_e32 v15, vcc, 0, v15, vcc
	s_waitcnt vmcnt(6)
	v_mov_b32_e32 v14, v218
	v_mov_b32_e32 v15, v219
	v_mov_b32_e32 v16, v220
	v_mov_b32_e32 v17, v221
	s_nop 0
	v_pk_fma_f32 v[18:19], v[18:19], v[0:1], v[14:15]
	v_add_u32_e32 v0, 5, v7
	v_ashrrev_i32_e32 v1, 31, v0
	v_lshlrev_b64 v[0:1], 13, v[0:1]
	v_lshl_add_u64 v[0:1], s[70:71], 0, v[0:1]
	v_lshl_add_u64 v[14:15], v[0:1], 0, v[96:97]
	v_pk_fma_f32 v[10:11], v[10:11], v[2:3], v[16:17]
	s_waitcnt vmcnt(5)
	v_mov_b32_e32 v0, v222
	v_mov_b32_e32 v1, v223
	v_mov_b32_e32 v2, v224
	v_mov_b32_e32 v3, v225
	v_add_co_u32_e32 v14, vcc, s7, v14
	s_nop 1
	v_addc_co_u32_e32 v15, vcc, 0, v15, vcc
	s_waitcnt vmcnt(4)
	v_mov_b32_e32 v14, v226
	v_mov_b32_e32 v15, v227
	v_mov_b32_e32 v16, v228
	v_mov_b32_e32 v17, v229
	s_nop 0
	v_pk_fma_f32 v[2:3], v[10:11], v[2:3], v[16:17]
	v_pk_fma_f32 v[10:11], v[18:19], v[0:1], v[14:15]
	v_add_u32_e32 v0, 6, v7
	v_ashrrev_i32_e32 v1, 31, v0
	v_lshlrev_b64 v[0:1], 13, v[0:1]
	v_lshl_add_u64 v[0:1], s[70:71], 0, v[0:1]
	v_lshl_add_u64 v[0:1], v[0:1], 0, v[96:97]
	s_waitcnt vmcnt(3)
	v_mov_b32_e32 v14, v230
	v_mov_b32_e32 v15, v231
	v_mov_b32_e32 v16, v232
	v_mov_b32_e32 v17, v233
	v_add_co_u32_e32 v0, vcc, s7, v0
	s_nop 1
	v_addc_co_u32_e32 v1, vcc, 0, v1, vcc
	s_waitcnt vmcnt(2)
	v_mov_b32_e32 v18, v234
	v_mov_b32_e32 v19, v235
	v_mov_b32_e32 v20, v236
	v_mov_b32_e32 v21, v237
	s_nop 0
	v_pk_fma_f32 v[0:1], v[2:3], v[16:17], v[20:21]
	v_add_u32_e32 v2, 7, v7
	v_ashrrev_i32_e32 v3, 31, v2
	v_lshlrev_b64 v[2:3], 13, v[2:3]
	v_lshl_add_u64 v[2:3], s[70:71], 0, v[2:3]
	v_lshl_add_u64 v[2:3], v[2:3], 0, v[96:97]
	v_pk_fma_f32 v[10:11], v[10:11], v[14:15], v[18:19]
	s_waitcnt vmcnt(1)
	v_mov_b32_e32 v14, v238
	v_mov_b32_e32 v15, v239
	v_mov_b32_e32 v16, v240
	v_mov_b32_e32 v17, v241
	v_add_co_u32_e32 v2, vcc, s7, v2
	s_nop 1
	v_addc_co_u32_e32 v3, vcc, 0, v3, vcc
	s_waitcnt vmcnt(0)
	v_mov_b32_e32 v18, v242
	v_mov_b32_e32 v19, v243
	v_mov_b32_e32 v20, v244
	v_mov_b32_e32 v21, v245
	v_cmp_eq_u32_e32 vcc, s2, v5
	s_or_b64 s[94:95], vcc, s[94:95]
	s_nop 0
	v_pk_fma_f32 v[2:3], v[0:1], v[16:17], v[20:21]
	v_pk_fma_f32 v[0:1], v[10:11], v[14:15], v[18:19]
	s_andn2_b64 exec, exec, s[94:95]
	s_cbranch_execnz .LBB0_245
	s_or_b64 exec, exec, s[94:95]

.LBB0_254:
	v_lshl_add_u64 v[34:35], v[6:7], 0, s[92:93]
	v_add_co_u32_e32 v36, vcc, 0x22cb5000, v34
	s_nop 1
	v_addc_co_u32_e32 v37, vcc, 0, v35, vcc
	v_add_co_u32_e32 v38, vcc, 0x24d35000, v34
	global_load_dwordx2 v[40:41], v[36:37], off
	s_nop 0
	v_addc_co_u32_e32 v39, vcc, 0, v35, vcc
	global_load_dwordx2 v[42:43], v[38:39], off
	global_load_dwordx2 v[44:45], v[36:37], off offset:2048
	global_load_dwordx2 v[46:47], v[38:39], off offset:2048
	v_add_co_u32_e32 v38, vcc, s2, v34
	s_nop 1
	v_addc_co_u32_e32 v39, vcc, 0, v35, vcc
	v_add_co_u32_e32 v48, vcc, s8, v34
	s_nop 1
	v_addc_co_u32_e32 v49, vcc, 0, v35, vcc
	v_add_co_u32_e32 v50, vcc, s7, v34
	global_load_dwordx2 v[52:53], v[48:49], off offset:-4096
	s_nop 0
	v_addc_co_u32_e32 v51, vcc, 0, v35, vcc
	v_add_co_u32_e32 v54, vcc, s9, v34
	s_nop 1
	v_addc_co_u32_e32 v55, vcc, 0, v35, vcc
	global_load_dwordx2 v[56:57], v[54:55], off offset:-4096
	global_load_dwordx2 v[58:59], v[38:39], off offset:2048
	global_load_dwordx2 v[60:61], v[50:51], off offset:2048
	global_load_dwordx2 v[62:63], v[48:49], off
	global_load_dwordx2 v[102:103], v[54:55], off
	global_load_dwordx2 v[104:105], v[48:49], off offset:2048
	global_load_dwordx2 v[106:107], v[54:55], off offset:2048
	v_add_co_u32_e32 v54, vcc, s10, v34
	s_nop 1
	v_addc_co_u32_e32 v55, vcc, 0, v35, vcc
	v_add_co_u32_e32 v34, vcc, s11, v34
	global_load_dwordx2 v[108:109], v[54:55], off
	s_nop 0
	v_addc_co_u32_e32 v35, vcc, 0, v35, vcc
	global_load_dwordx2 v[110:111], v[34:35], off
	global_load_dwordx2 v[210:211], v[54:55], off offset:2048
	global_load_dwordx2 v[212:213], v[34:35], off offset:2048
	v_lshl_add_u64 v[10:11], v[6:7], 0, s[92:93]
	v_add_co_u32_e32 v14, vcc, 0x22cb5000, v10
	s_add_u32 s92, s92, 0x4000
	s_nop 0
	v_addc_co_u32_e32 v15, vcc, 0, v11, vcc
	v_add_co_u32_e32 v16, vcc, 0x24d35000, v10
	s_waitcnt vmcnt(15)
	v_mov_b32_e32 v12, v40
	v_mov_b32_e32 v13, v41
	s_nop 0
	v_addc_co_u32_e32 v17, vcc, 0, v11, vcc
	s_waitcnt vmcnt(14)
	v_mov_b32_e32 v18, v42
	v_mov_b32_e32 v19, v43
	s_addc_u32 s93, s93, 0
	s_nop 0
	v_lshlrev_b32_e32 v22, 16, v12
	v_and_b32_e32 v9, 0xffff0000, v12
	v_mul_f32_e32 v9, 0x3fb8aa3b, v9
	s_nop 0
	v_and_b32_e32 v21, 0xffff0000, v18
	v_lshlrev_b32_e32 v20, 16, v18
	v_mul_f32_e32 v18, 0x3fb8aa3b, v22
	v_exp_f32_e32 v22, v18
	v_and_b32_e32 v26, 0xffff0000, v13
	v_lshlrev_b32_e32 v13, 16, v13
	v_lshlrev_b32_e32 v12, 16, v19
	v_fma_f32 v18, -v22, v22, 1.0
	v_max_f32_e32 v18, 0, v18
	v_cmp_gt_f32_e32 vcc, s97, v18
	v_mul_f32_e32 v23, 0x4f800000, v18
	s_nop 0
	v_cndmask_b32_e32 v18, v18, v23, vcc
	v_sqrt_f32_e32 v23, v18
	s_nop 0
	v_add_u32_e32 v24, -1, v23
	v_fma_f32 v25, -v24, v23, v18
	v_cmp_ge_f32_e64 s[0:1], 0, v25
	v_add_u32_e32 v25, 1, v23
	s_nop 0
	v_cndmask_b32_e64 v24, v23, v24, s[0:1]
	v_fma_f32 v23, -v25, v23, v18
	v_cmp_lt_f32_e64 s[0:1], 0, v23
	s_nop 1
	v_cndmask_b32_e64 v23, v24, v25, s[0:1]
	v_mul_f32_e32 v24, 0x37800000, v23
	v_cndmask_b32_e32 v23, v23, v24, vcc
	v_cmp_class_f32_e32 vcc, v18, v149
	s_nop 1
	v_cndmask_b32_e32 v24, v23, v18, vcc
	v_exp_f32_e32 v23, v9
	s_nop 0
	v_fma_f32 v9, -v23, v23, 1.0
	v_max_f32_e32 v9, 0, v9
	v_cmp_gt_f32_e32 vcc, s97, v9
	v_mul_f32_e32 v18, 0x4f800000, v9
	s_nop 0
	v_cndmask_b32_e32 v9, v9, v18, vcc
	v_sqrt_f32_e32 v18, v9
	s_nop 0
	v_add_u32_e32 v25, -1, v18
	v_fma_f32 v27, -v25, v18, v9
	v_cmp_ge_f32_e64 s[0:1], 0, v27
	v_add_u32_e32 v27, 1, v18
	s_nop 0
	v_cndmask_b32_e64 v25, v18, v25, s[0:1]
	v_fma_f32 v18, -v27, v18, v9
	v_cmp_lt_f32_e64 s[0:1], 0, v18
	s_nop 1
	v_cndmask_b32_e64 v18, v25, v27, s[0:1]
	v_mul_f32_e32 v25, 0x37800000, v18
	v_cndmask_b32_e32 v18, v18, v25, vcc
	v_cmp_class_f32_e32 vcc, v9, v149
	s_nop 1
	v_cndmask_b32_e32 v25, v18, v9, vcc
	v_pk_mul_f32 v[20:21], v[24:25], v[20:21]
	v_mul_f32_e32 v9, 0x3fb8aa3b, v13
	v_pk_fma_f32 v[0:1], v[0:1], v[22:23], v[20:21]
	v_exp_f32_e32 v20, v9
	s_nop 0
	v_fma_f32 v9, -v20, v20, 1.0
	v_max_f32_e32 v9, 0, v9
	v_cmp_gt_f32_e32 vcc, s97, v9
	v_mul_f32_e32 v13, 0x4f800000, v9
	s_nop 0
	v_cndmask_b32_e32 v9, v9, v13, vcc
	v_sqrt_f32_e32 v13, v9
	s_nop 0
	v_add_u32_e32 v18, -1, v13
	v_fma_f32 v21, -v18, v13, v9
	v_cmp_ge_f32_e64 s[0:1], 0, v21
	v_add_u32_e32 v21, 1, v13
	s_nop 0
	v_cndmask_b32_e64 v18, v13, v18, s[0:1]
	v_fma_f32 v13, -v21, v13, v9
	v_cmp_lt_f32_e64 s[0:1], 0, v13
	s_nop 1
	v_cndmask_b32_e64 v13, v18, v21, s[0:1]
	v_mul_f32_e32 v18, 0x37800000, v13
	v_cndmask_b32_e32 v13, v13, v18, vcc
	v_cmp_class_f32_e32 vcc, v9, v149
	s_nop 1
	v_cndmask_b32_e32 v18, v13, v9, vcc
	v_mul_f32_e32 v9, 0x3fb8aa3b, v26
	v_exp_f32_e32 v21, v9
	v_and_b32_e32 v13, 0xffff0000, v19
	v_fma_f32 v9, -v21, v21, 1.0
	v_max_f32_e32 v9, 0, v9
	v_cmp_gt_f32_e32 vcc, s97, v9
	v_mul_f32_e32 v19, 0x4f800000, v9
	s_nop 0
	v_cndmask_b32_e32 v9, v9, v19, vcc
	v_sqrt_f32_e32 v19, v9
	s_nop 0
	v_add_u32_e32 v22, -1, v19
	v_fma_f32 v23, -v22, v19, v9
	v_cmp_ge_f32_e64 s[0:1], 0, v23
	v_add_u32_e32 v23, 1, v19
	s_nop 0
	v_cndmask_b32_e64 v22, v19, v22, s[0:1]
	v_fma_f32 v19, -v23, v19, v9
	v_cmp_lt_f32_e64 s[0:1], 0, v19
	s_nop 1
	v_cndmask_b32_e64 v19, v22, v23, s[0:1]
	v_mul_f32_e32 v22, 0x37800000, v19
	v_cndmask_b32_e32 v19, v19, v22, vcc
	v_cmp_class_f32_e32 vcc, v9, v149
	s_mov_b32 s0, 0x188b1000
	s_nop 0
	v_cndmask_b32_e32 v19, v19, v9, vcc
	v_pk_mul_f32 v[12:13], v[18:19], v[12:13]
	v_and_b32_sdwa v18, v1, v154 dst_sel:DWORD dst_unused:UNUSED_PAD src0_sel:WORD_1 src1_sel:DWORD
	v_pk_fma_f32 v[2:3], v[2:3], v[20:21], v[12:13]
	v_and_b32_sdwa v12, v0, v154 dst_sel:DWORD dst_unused:UNUSED_PAD src0_sel:WORD_1 src1_sel:DWORD
	v_and_b32_sdwa v13, v3, v154 dst_sel:DWORD dst_unused:UNUSED_PAD src0_sel:WORD_1 src1_sel:DWORD
	v_add3_u32 v18, v1, v18, s33
	v_add_co_u32_e32 v20, vcc, s0, v10
	v_and_b32_sdwa v9, v2, v154 dst_sel:DWORD dst_unused:UNUSED_PAD src0_sel:WORD_1 src1_sel:DWORD
	v_add3_u32 v12, v0, v12, s33
	v_add3_u32 v13, v3, v13, s33
	v_and_b32_e32 v18, 0xffff0000, v18
	v_addc_co_u32_e32 v21, vcc, 0, v11, vcc
	s_mov_b32 s0, 0x188b2000
	v_add3_u32 v9, v2, v9, s33
	v_and_b32_e32 v13, 0xffff0000, v13
	v_or_b32_sdwa v18, v18, v12 dst_sel:DWORD dst_unused:UNUSED_PAD src0_sel:DWORD src1_sel:WORD_1
	v_add_co_u32_e32 v12, vcc, s0, v10
	v_or_b32_sdwa v19, v13, v9 dst_sel:DWORD dst_unused:UNUSED_PAD src0_sel:DWORD src1_sel:WORD_1
	s_nop 0
	v_addc_co_u32_e32 v13, vcc, 0, v11, vcc
	global_store_dwordx2 v[12:13], v[18:19], off offset:-4096
	s_waitcnt vmcnt(14)
	v_mov_b32_e32 v14, v44
	v_mov_b32_e32 v15, v45
	s_nop 0
	s_waitcnt vmcnt(13)
	v_mov_b32_e32 v16, v46
	v_mov_b32_e32 v17, v47
	s_nop 0
	v_lshlrev_b32_e32 v22, 16, v14
	s_nop 0
	v_and_b32_e32 v19, 0xffff0000, v16
	v_lshlrev_b32_e32 v18, 16, v16
	v_mul_f32_e32 v16, 0x3fb8aa3b, v22
	v_exp_f32_e32 v22, v16
	v_and_b32_e32 v9, 0xffff0000, v14
	v_mul_f32_e32 v9, 0x3fb8aa3b, v9
	v_and_b32_e32 v26, 0xffff0000, v15
	v_fma_f32 v16, -v22, v22, 1.0
	v_max_f32_e32 v16, 0, v16
	v_cmp_gt_f32_e32 vcc, s97, v16
	v_mul_f32_e32 v23, 0x4f800000, v16
	v_lshlrev_b32_e32 v15, 16, v15
	v_cndmask_b32_e32 v16, v16, v23, vcc
	v_sqrt_f32_e32 v23, v16
	v_lshlrev_b32_e32 v14, 16, v17
	v_add_u32_e32 v24, -1, v23
	v_fma_f32 v25, -v24, v23, v16
	v_cmp_ge_f32_e64 s[0:1], 0, v25
	v_add_u32_e32 v25, 1, v23
	s_nop 0
	v_cndmask_b32_e64 v24, v23, v24, s[0:1]
	v_fma_f32 v23, -v25, v23, v16
	v_cmp_lt_f32_e64 s[0:1], 0, v23
	s_nop 1
	v_cndmask_b32_e64 v23, v24, v25, s[0:1]
	v_mul_f32_e32 v24, 0x37800000, v23
	v_cndmask_b32_e32 v23, v23, v24, vcc
	v_cmp_class_f32_e32 vcc, v16, v149
	s_nop 1
	v_cndmask_b32_e32 v24, v23, v16, vcc
	v_exp_f32_e32 v23, v9
	s_nop 0
	v_fma_f32 v9, -v23, v23, 1.0
	v_max_f32_e32 v9, 0, v9
	v_cmp_gt_f32_e32 vcc, s97, v9
	v_mul_f32_e32 v16, 0x4f800000, v9
	s_nop 0
	v_cndmask_b32_e32 v9, v9, v16, vcc
	v_sqrt_f32_e32 v16, v9
	s_nop 0
	v_add_u32_e32 v25, -1, v16
	v_fma_f32 v27, -v25, v16, v9
	v_cmp_ge_f32_e64 s[0:1], 0, v27
	v_add_u32_e32 v27, 1, v16
	s_nop 0
	v_cndmask_b32_e64 v25, v16, v25, s[0:1]
	v_fma_f32 v16, -v27, v16, v9
	v_cmp_lt_f32_e64 s[0:1], 0, v16
	s_nop 1
	v_cndmask_b32_e64 v16, v25, v27, s[0:1]
	v_mul_f32_e32 v25, 0x37800000, v16
	v_cndmask_b32_e32 v16, v16, v25, vcc
	v_cmp_class_f32_e32 vcc, v9, v149
	s_nop 1
	v_cndmask_b32_e32 v25, v16, v9, vcc
	v_pk_mul_f32 v[18:19], v[24:25], v[18:19]
	s_nop 0
	v_pk_fma_f32 v[18:19], v[0:1], v[22:23], v[18:19]
	v_mul_f32_e32 v0, 0x3fb8aa3b, v15
	v_exp_f32_e32 v0, v0
	s_nop 0
	v_fma_f32 v1, -v0, v0, 1.0
	v_max_f32_e32 v1, 0, v1
	v_cmp_gt_f32_e32 vcc, s97, v1
	v_mul_f32_e32 v9, 0x4f800000, v1
	s_nop 0
	v_cndmask_b32_e32 v1, v1, v9, vcc
	v_sqrt_f32_e32 v9, v1
	s_nop 0
	v_add_u32_e32 v15, -1, v9
	v_fma_f32 v16, -v15, v9, v1
	v_cmp_ge_f32_e64 s[0:1], 0, v16
	v_add_u32_e32 v16, 1, v9
	s_nop 0
	v_cndmask_b32_e64 v15, v9, v15, s[0:1]
	v_fma_f32 v9, -v16, v9, v1
	v_cmp_lt_f32_e64 s[0:1], 0, v9
	s_nop 1
	v_cndmask_b32_e64 v9, v15, v16, s[0:1]
	v_mul_f32_e32 v15, 0x37800000, v9
	v_cndmask_b32_e32 v9, v9, v15, vcc
	v_cmp_class_f32_e32 vcc, v1, v149
	v_and_b32_e32 v15, 0xffff0000, v17
	s_nop 0
	v_cndmask_b32_e32 v16, v9, v1, vcc
	v_mul_f32_e32 v1, 0x3fb8aa3b, v26
	v_exp_f32_e32 v1, v1
	s_nop 0
	v_fma_f32 v9, -v1, v1, 1.0
	v_max_f32_e32 v9, 0, v9
	v_cmp_gt_f32_e32 vcc, s97, v9
	v_mul_f32_e32 v17, 0x4f800000, v9
	s_nop 0
	v_cndmask_b32_e32 v9, v9, v17, vcc
	v_sqrt_f32_e32 v17, v9
	s_nop 0
	v_add_u32_e32 v22, -1, v17
	v_fma_f32 v23, -v22, v17, v9
	v_cmp_ge_f32_e64 s[0:1], 0, v23
	v_add_u32_e32 v23, 1, v17
	s_nop 0
	v_cndmask_b32_e64 v22, v17, v22, s[0:1]
	v_fma_f32 v17, -v23, v17, v9
	v_cmp_lt_f32_e64 s[0:1], 0, v17
	s_nop 1
	v_cndmask_b32_e64 v17, v22, v23, s[0:1]
	v_mul_f32_e32 v22, 0x37800000, v17
	v_cndmask_b32_e32 v17, v17, v22, vcc
	v_cmp_class_f32_e32 vcc, v9, v149
	s_nop 1
	v_cndmask_b32_e32 v17, v17, v9, vcc
	v_pk_mul_f32 v[14:15], v[16:17], v[14:15]
	v_add_co_u32_e32 v16, vcc, s2, v10
	v_pk_fma_f32 v[14:15], v[2:3], v[0:1], v[14:15]
	v_and_b32_sdwa v1, v18, v154 dst_sel:DWORD dst_unused:UNUSED_PAD src0_sel:WORD_1 src1_sel:DWORD
	v_add3_u32 v2, v18, v1, s33
	v_and_b32_sdwa v1, v15, v154 dst_sel:DWORD dst_unused:UNUSED_PAD src0_sel:WORD_1 src1_sel:DWORD
	v_and_b32_sdwa v3, v19, v154 dst_sel:DWORD dst_unused:UNUSED_PAD src0_sel:WORD_1 src1_sel:DWORD
	v_and_b32_sdwa v0, v14, v154 dst_sel:DWORD dst_unused:UNUSED_PAD src0_sel:WORD_1 src1_sel:DWORD
	v_add3_u32 v1, v15, v1, s33
	v_add3_u32 v3, v19, v3, s33
	v_add3_u32 v0, v14, v0, s33
	v_and_b32_e32 v1, 0xffff0000, v1
	v_and_b32_e32 v3, 0xffff0000, v3
	v_or_b32_sdwa v1, v1, v0 dst_sel:DWORD dst_unused:UNUSED_PAD src0_sel:DWORD src1_sel:WORD_1
	v_or_b32_sdwa v0, v3, v2 dst_sel:DWORD dst_unused:UNUSED_PAD src0_sel:DWORD src1_sel:WORD_1
	v_addc_co_u32_e32 v17, vcc, 0, v11, vcc
	global_store_dwordx2 v[20:21], v[0:1], off offset:2048
	v_add_co_u32_e32 v0, vcc, s8, v10
	s_nop 1
	v_addc_co_u32_e32 v1, vcc, 0, v11, vcc
	v_add_co_u32_e32 v22, vcc, s7, v10
	s_waitcnt vmcnt(13)
	v_mov_b32_e32 v20, v52
	v_mov_b32_e32 v21, v53
	s_nop 0
	v_addc_co_u32_e32 v23, vcc, 0, v11, vcc
	v_add_co_u32_e32 v2, vcc, s9, v10
	s_nop 1
	v_addc_co_u32_e32 v3, vcc, 0, v11, vcc
	s_waitcnt vmcnt(12)
	v_mov_b32_e32 v24, v56
	v_mov_b32_e32 v25, v57
	s_nop 0
	v_lshlrev_b32_e32 v28, 16, v20
	v_and_b32_e32 v9, 0xffff0000, v20
	v_mul_f32_e32 v9, 0x3fb8aa3b, v9
	v_and_b32_e32 v32, 0xffff0000, v21
	v_lshlrev_b32_e32 v21, 16, v21
	s_nop 0
	v_and_b32_e32 v27, 0xffff0000, v24
	v_lshlrev_b32_e32 v26, 16, v24
	v_mul_f32_e32 v24, 0x3fb8aa3b, v28
	v_exp_f32_e32 v28, v24
	v_lshlrev_b32_e32 v20, 16, v25
	v_fma_f32 v24, -v28, v28, 1.0
	v_max_f32_e32 v24, 0, v24
	v_cmp_gt_f32_e32 vcc, s97, v24
	v_mul_f32_e32 v29, 0x4f800000, v24
	s_nop 0
	v_cndmask_b32_e32 v24, v24, v29, vcc
	v_sqrt_f32_e32 v29, v24
	s_nop 0
	v_add_u32_e32 v30, -1, v29
	v_fma_f32 v31, -v30, v29, v24
	v_cmp_ge_f32_e64 s[0:1], 0, v31
	v_add_u32_e32 v31, 1, v29
	s_nop 0
	v_cndmask_b32_e64 v30, v29, v30, s[0:1]
	v_fma_f32 v29, -v31, v29, v24
	v_cmp_lt_f32_e64 s[0:1], 0, v29
	s_nop 1
	v_cndmask_b32_e64 v29, v30, v31, s[0:1]
	v_mul_f32_e32 v30, 0x37800000, v29
	v_cndmask_b32_e32 v29, v29, v30, vcc
	v_cmp_class_f32_e32 vcc, v24, v149
	s_nop 1
	v_cndmask_b32_e32 v30, v29, v24, vcc
	v_exp_f32_e32 v29, v9
	s_nop 0
	v_fma_f32 v9, -v29, v29, 1.0
	v_max_f32_e32 v9, 0, v9
	v_cmp_gt_f32_e32 vcc, s97, v9
	v_mul_f32_e32 v24, 0x4f800000, v9
	s_nop 0
	v_cndmask_b32_e32 v9, v9, v24, vcc
	v_sqrt_f32_e32 v24, v9
	s_nop 0
	v_add_u32_e32 v31, -1, v24
	v_fma_f32 v33, -v31, v24, v9
	v_cmp_ge_f32_e64 s[0:1], 0, v33
	v_add_u32_e32 v33, 1, v24
	s_nop 0
	v_cndmask_b32_e64 v31, v24, v31, s[0:1]
	v_fma_f32 v24, -v33, v24, v9
	v_cmp_lt_f32_e64 s[0:1], 0, v24
	s_nop 1
	v_cndmask_b32_e64 v24, v31, v33, s[0:1]
	v_mul_f32_e32 v31, 0x37800000, v24
	v_cndmask_b32_e32 v24, v24, v31, vcc
	v_cmp_class_f32_e32 vcc, v9, v149
	s_nop 1
	v_cndmask_b32_e32 v31, v24, v9, vcc
	v_pk_mul_f32 v[26:27], v[30:31], v[26:27]
	v_mul_f32_e32 v9, 0x3fb8aa3b, v21
	v_pk_fma_f32 v[18:19], v[18:19], v[28:29], v[26:27]
	v_exp_f32_e32 v26, v9
	s_nop 0
	v_fma_f32 v9, -v26, v26, 1.0
	v_max_f32_e32 v9, 0, v9
	v_cmp_gt_f32_e32 vcc, s97, v9
	v_mul_f32_e32 v21, 0x4f800000, v9
	s_nop 0
	v_cndmask_b32_e32 v9, v9, v21, vcc
	v_sqrt_f32_e32 v21, v9
	s_nop 0
	v_add_u32_e32 v24, -1, v21
	v_fma_f32 v27, -v24, v21, v9
	v_cmp_ge_f32_e64 s[0:1], 0, v27
	v_add_u32_e32 v27, 1, v21
	s_nop 0
	v_cndmask_b32_e64 v24, v21, v24, s[0:1]
	v_fma_f32 v21, -v27, v21, v9
	v_cmp_lt_f32_e64 s[0:1], 0, v21
	s_nop 1
	v_cndmask_b32_e64 v21, v24, v27, s[0:1]
	v_mul_f32_e32 v24, 0x37800000, v21
	v_cndmask_b32_e32 v21, v21, v24, vcc
	v_cmp_class_f32_e32 vcc, v9, v149
	s_nop 1
	v_cndmask_b32_e32 v24, v21, v9, vcc
	v_mul_f32_e32 v9, 0x3fb8aa3b, v32
	v_exp_f32_e32 v27, v9
	v_and_b32_e32 v21, 0xffff0000, v25
	v_fma_f32 v9, -v27, v27, 1.0
	v_max_f32_e32 v9, 0, v9
	v_cmp_gt_f32_e32 vcc, s97, v9
	v_mul_f32_e32 v25, 0x4f800000, v9
	s_nop 0
	v_cndmask_b32_e32 v9, v9, v25, vcc
	v_sqrt_f32_e32 v25, v9
	s_nop 0
	v_add_u32_e32 v28, -1, v25
	v_fma_f32 v29, -v28, v25, v9
	v_cmp_ge_f32_e64 s[0:1], 0, v29
	v_add_u32_e32 v29, 1, v25
	s_nop 0
	v_cndmask_b32_e64 v28, v25, v28, s[0:1]
	v_fma_f32 v25, -v29, v25, v9
	v_cmp_lt_f32_e64 s[0:1], 0, v25
	s_nop 1
	v_cndmask_b32_e64 v25, v28, v29, s[0:1]
	v_mul_f32_e32 v28, 0x37800000, v25
	v_cndmask_b32_e32 v25, v25, v28, vcc
	v_cmp_class_f32_e32 vcc, v9, v149
	s_nop 1
	v_cndmask_b32_e32 v25, v25, v9, vcc
	v_pk_mul_f32 v[20:21], v[24:25], v[20:21]
	v_and_b32_sdwa v24, v19, v154 dst_sel:DWORD dst_unused:UNUSED_PAD src0_sel:WORD_1 src1_sel:DWORD
	v_pk_fma_f32 v[14:15], v[14:15], v[26:27], v[20:21]
	v_and_b32_sdwa v20, v18, v154 dst_sel:DWORD dst_unused:UNUSED_PAD src0_sel:WORD_1 src1_sel:DWORD
	v_and_b32_sdwa v21, v15, v154 dst_sel:DWORD dst_unused:UNUSED_PAD src0_sel:WORD_1 src1_sel:DWORD
	v_and_b32_sdwa v9, v14, v154 dst_sel:DWORD dst_unused:UNUSED_PAD src0_sel:WORD_1 src1_sel:DWORD
	v_add3_u32 v21, v15, v21, s33
	v_add3_u32 v24, v19, v24, s33
	v_add3_u32 v20, v18, v20, s33
	v_add3_u32 v9, v14, v9, s33
	v_and_b32_e32 v21, 0xffff0000, v21
	v_and_b32_e32 v24, 0xffff0000, v24
	v_or_b32_sdwa v21, v21, v9 dst_sel:DWORD dst_unused:UNUSED_PAD src0_sel:DWORD src1_sel:WORD_1
	v_or_b32_sdwa v20, v24, v20 dst_sel:DWORD dst_unused:UNUSED_PAD src0_sel:DWORD src1_sel:WORD_1
	global_store_dwordx2 v[12:13], v[20:21], off
	s_waitcnt vmcnt(12)
	v_mov_b32_e32 v16, v58
	v_mov_b32_e32 v17, v59
	s_nop 0
	s_waitcnt vmcnt(11)
	v_mov_b32_e32 v20, v60
	v_mov_b32_e32 v21, v61
	s_nop 0
	v_lshlrev_b32_e32 v24, 16, v16
	s_nop 0
	v_and_b32_e32 v23, 0xffff0000, v20
	v_lshlrev_b32_e32 v22, 16, v20
	v_mul_f32_e32 v20, 0x3fb8aa3b, v24
	v_exp_f32_e32 v24, v20
	v_and_b32_e32 v9, 0xffff0000, v16
	v_mul_f32_e32 v9, 0x3fb8aa3b, v9
	v_and_b32_e32 v28, 0xffff0000, v17
	v_fma_f32 v20, -v24, v24, 1.0
	v_max_f32_e32 v20, 0, v20
	v_cmp_gt_f32_e32 vcc, s97, v20
	v_mul_f32_e32 v25, 0x4f800000, v20
	v_lshlrev_b32_e32 v17, 16, v17
	v_cndmask_b32_e32 v20, v20, v25, vcc
	v_sqrt_f32_e32 v25, v20
	v_lshlrev_b32_e32 v16, 16, v21
	v_add_u32_e32 v26, -1, v25
	v_fma_f32 v27, -v26, v25, v20
	v_cmp_ge_f32_e64 s[0:1], 0, v27
	v_add_u32_e32 v27, 1, v25
	s_nop 0
	v_cndmask_b32_e64 v26, v25, v26, s[0:1]
	v_fma_f32 v25, -v27, v25, v20
	v_cmp_lt_f32_e64 s[0:1], 0, v25
	s_nop 1
	v_cndmask_b32_e64 v25, v26, v27, s[0:1]
	v_mul_f32_e32 v26, 0x37800000, v25
	v_cndmask_b32_e32 v25, v25, v26, vcc
	v_cmp_class_f32_e32 vcc, v20, v149
	s_nop 1
	v_cndmask_b32_e32 v26, v25, v20, vcc
	v_exp_f32_e32 v25, v9
	s_nop 0
	v_fma_f32 v9, -v25, v25, 1.0
	v_max_f32_e32 v9, 0, v9
	v_cmp_gt_f32_e32 vcc, s97, v9
	v_mul_f32_e32 v20, 0x4f800000, v9
	s_nop 0
	v_cndmask_b32_e32 v9, v9, v20, vcc
	v_sqrt_f32_e32 v20, v9
	s_nop 0
	v_add_u32_e32 v27, -1, v20
	v_fma_f32 v29, -v27, v20, v9
	v_cmp_ge_f32_e64 s[0:1], 0, v29
	v_add_u32_e32 v29, 1, v20
	s_nop 0
	v_cndmask_b32_e64 v27, v20, v27, s[0:1]
	v_fma_f32 v20, -v29, v20, v9
	v_cmp_lt_f32_e64 s[0:1], 0, v20
	s_nop 1
	v_cndmask_b32_e64 v20, v27, v29, s[0:1]
	v_mul_f32_e32 v27, 0x37800000, v20
	v_cndmask_b32_e32 v20, v20, v27, vcc
	v_cmp_class_f32_e32 vcc, v9, v149
	s_nop 1
	v_cndmask_b32_e32 v27, v20, v9, vcc
	v_pk_mul_f32 v[22:23], v[26:27], v[22:23]
	v_mul_f32_e32 v9, 0x3fb8aa3b, v17
	v_pk_fma_f32 v[18:19], v[18:19], v[24:25], v[22:23]
	v_exp_f32_e32 v22, v9
	s_nop 0
	v_fma_f32 v9, -v22, v22, 1.0
	v_max_f32_e32 v9, 0, v9
	v_cmp_gt_f32_e32 vcc, s97, v9
	v_mul_f32_e32 v17, 0x4f800000, v9
	s_nop 0
	v_cndmask_b32_e32 v9, v9, v17, vcc
	v_sqrt_f32_e32 v17, v9
	s_nop 0
	v_add_u32_e32 v20, -1, v17
	v_fma_f32 v23, -v20, v17, v9
	v_cmp_ge_f32_e64 s[0:1], 0, v23
	v_add_u32_e32 v23, 1, v17
	s_nop 0
	v_cndmask_b32_e64 v20, v17, v20, s[0:1]
	v_fma_f32 v17, -v23, v17, v9
	v_cmp_lt_f32_e64 s[0:1], 0, v17
	s_nop 1
	v_cndmask_b32_e64 v17, v20, v23, s[0:1]
	v_mul_f32_e32 v20, 0x37800000, v17
	v_cndmask_b32_e32 v17, v17, v20, vcc
	v_cmp_class_f32_e32 vcc, v9, v149
	s_nop 1
	v_cndmask_b32_e32 v20, v17, v9, vcc
	v_mul_f32_e32 v9, 0x3fb8aa3b, v28
	v_exp_f32_e32 v23, v9
	v_and_b32_e32 v17, 0xffff0000, v21
	v_fma_f32 v9, -v23, v23, 1.0
	v_max_f32_e32 v9, 0, v9
	v_cmp_gt_f32_e32 vcc, s97, v9
	v_mul_f32_e32 v21, 0x4f800000, v9
	s_nop 0
	v_cndmask_b32_e32 v9, v9, v21, vcc
	v_sqrt_f32_e32 v21, v9
	s_nop 0
	v_add_u32_e32 v24, -1, v21
	v_fma_f32 v25, -v24, v21, v9
	v_cmp_ge_f32_e64 s[0:1], 0, v25
	v_add_u32_e32 v25, 1, v21
	s_nop 0
	v_cndmask_b32_e64 v24, v21, v24, s[0:1]
	v_fma_f32 v21, -v25, v21, v9
	v_cmp_lt_f32_e64 s[0:1], 0, v21
	s_nop 1
	v_cndmask_b32_e64 v21, v24, v25, s[0:1]
	v_mul_f32_e32 v24, 0x37800000, v21
	v_cndmask_b32_e32 v21, v21, v24, vcc
	v_cmp_class_f32_e32 vcc, v9, v149
	s_nop 1
	v_cndmask_b32_e32 v21, v21, v9, vcc
	v_pk_mul_f32 v[16:17], v[20:21], v[16:17]
	v_and_b32_sdwa v20, v19, v154 dst_sel:DWORD dst_unused:UNUSED_PAD src0_sel:WORD_1 src1_sel:DWORD
	v_pk_fma_f32 v[14:15], v[14:15], v[22:23], v[16:17]
	v_and_b32_sdwa v16, v18, v154 dst_sel:DWORD dst_unused:UNUSED_PAD src0_sel:WORD_1 src1_sel:DWORD
	v_and_b32_sdwa v17, v15, v154 dst_sel:DWORD dst_unused:UNUSED_PAD src0_sel:WORD_1 src1_sel:DWORD
	v_and_b32_sdwa v9, v14, v154 dst_sel:DWORD dst_unused:UNUSED_PAD src0_sel:WORD_1 src1_sel:DWORD
	v_add3_u32 v17, v15, v17, s33
	v_add3_u32 v20, v19, v20, s33
	v_add3_u32 v16, v18, v16, s33
	v_add3_u32 v9, v14, v9, s33
	v_and_b32_e32 v17, 0xffff0000, v17
	v_and_b32_e32 v20, 0xffff0000, v20
	v_or_b32_sdwa v17, v17, v9 dst_sel:DWORD dst_unused:UNUSED_PAD src0_sel:DWORD src1_sel:WORD_1
	v_or_b32_sdwa v16, v20, v16 dst_sel:DWORD dst_unused:UNUSED_PAD src0_sel:DWORD src1_sel:WORD_1
	global_store_dwordx2 v[12:13], v[16:17], off offset:2048
	s_waitcnt vmcnt(11)
	v_mov_b32_e32 v12, v62
	v_mov_b32_e32 v13, v63
	s_nop 0
	s_waitcnt vmcnt(10)
	v_mov_b32_e32 v16, v102
	v_mov_b32_e32 v17, v103
	s_nop 0
	v_and_b32_e32 v9, 0xffff0000, v12
	v_lshlrev_b32_e32 v12, 16, v12
	v_mul_f32_e32 v12, 0x3fb8aa3b, v12
	v_exp_f32_e32 v12, v12
	v_and_b32_e32 v24, 0xffff0000, v13
	v_lshlrev_b32_e32 v25, 16, v13
	v_mul_f32_e32 v9, 0x3fb8aa3b, v9
	v_fma_f32 v13, -v12, v12, 1.0
	v_max_f32_e32 v13, 0, v13
	v_cmp_gt_f32_e32 vcc, s97, v13
	v_mul_f32_e32 v22, 0x4f800000, v13
	s_nop 0
	v_and_b32_e32 v21, 0xffff0000, v16
	v_cndmask_b32_e32 v13, v13, v22, vcc
	v_sqrt_f32_e32 v22, v13
	v_lshlrev_b32_e32 v20, 16, v16
	v_lshlrev_b32_e32 v16, 16, v17
	v_and_b32_e32 v17, 0xffff0000, v17
	v_add_u32_e32 v23, -1, v22
	v_fma_f32 v26, -v23, v22, v13
	v_cmp_ge_f32_e64 s[0:1], 0, v26
	v_add_u32_e32 v26, 1, v22
	s_nop 0
	v_cndmask_b32_e64 v23, v22, v23, s[0:1]
	v_fma_f32 v22, -v26, v22, v13
	v_cmp_lt_f32_e64 s[0:1], 0, v22
	s_nop 1
	v_cndmask_b32_e64 v22, v23, v26, s[0:1]
	v_mul_f32_e32 v23, 0x37800000, v22
	v_cndmask_b32_e32 v22, v22, v23, vcc
	v_cmp_class_f32_e32 vcc, v13, v149
	s_nop 1
	v_cndmask_b32_e32 v22, v22, v13, vcc
	v_exp_f32_e32 v13, v9
	s_nop 0
	v_fma_f32 v9, -v13, v13, 1.0
	v_max_f32_e32 v9, 0, v9
	v_cmp_gt_f32_e32 vcc, s97, v9
	v_mul_f32_e32 v23, 0x4f800000, v9
	s_nop 0
	v_cndmask_b32_e32 v9, v9, v23, vcc
	v_sqrt_f32_e32 v23, v9
	s_nop 0
	v_add_u32_e32 v26, -1, v23
	v_fma_f32 v27, -v26, v23, v9
	v_cmp_ge_f32_e64 s[0:1], 0, v27
	v_add_u32_e32 v27, 1, v23
	s_nop 0
	v_cndmask_b32_e64 v26, v23, v26, s[0:1]
	v_fma_f32 v23, -v27, v23, v9
	v_cmp_lt_f32_e64 s[0:1], 0, v23
	s_nop 1
	v_cndmask_b32_e64 v23, v26, v27, s[0:1]
	v_mul_f32_e32 v26, 0x37800000, v23
	v_cndmask_b32_e32 v23, v23, v26, vcc
	v_cmp_class_f32_e32 vcc, v9, v149
	s_nop 1
	v_cndmask_b32_e32 v23, v23, v9, vcc
	v_pk_mul_f32 v[20:21], v[22:23], v[20:21]
	v_mul_f32_e32 v9, 0x3fb8aa3b, v25
	v_pk_fma_f32 v[12:13], v[18:19], v[12:13], v[20:21]
	v_exp_f32_e32 v18, v9
	s_nop 0
	v_fma_f32 v9, -v18, v18, 1.0
	v_max_f32_e32 v9, 0, v9
	v_cmp_gt_f32_e32 vcc, s97, v9
	v_mul_f32_e32 v19, 0x4f800000, v9
	s_nop 0
	v_cndmask_b32_e32 v9, v9, v19, vcc
	v_sqrt_f32_e32 v19, v9
	s_nop 0
	v_add_u32_e32 v20, -1, v19
	v_fma_f32 v21, -v20, v19, v9
	v_cmp_ge_f32_e64 s[0:1], 0, v21
	v_add_u32_e32 v21, 1, v19
	s_nop 0
	v_cndmask_b32_e64 v20, v19, v20, s[0:1]
	v_fma_f32 v19, -v21, v19, v9
	v_cmp_lt_f32_e64 s[0:1], 0, v19
	s_nop 1
	v_cndmask_b32_e64 v19, v20, v21, s[0:1]
	v_mul_f32_e32 v20, 0x37800000, v19
	v_cndmask_b32_e32 v19, v19, v20, vcc
	v_cmp_class_f32_e32 vcc, v9, v149
	s_nop 1
	v_cndmask_b32_e32 v20, v19, v9, vcc
	v_mul_f32_e32 v9, 0x3fb8aa3b, v24
	v_exp_f32_e32 v19, v9
	s_nop 0
	v_fma_f32 v9, -v19, v19, 1.0
	v_max_f32_e32 v9, 0, v9
	v_cmp_gt_f32_e32 vcc, s97, v9
	v_mul_f32_e32 v21, 0x4f800000, v9
	s_nop 0
	v_cndmask_b32_e32 v9, v9, v21, vcc
	v_sqrt_f32_e32 v21, v9
	s_nop 0
	v_add_u32_e32 v22, -1, v21
	v_fma_f32 v23, -v22, v21, v9
	v_cmp_ge_f32_e64 s[0:1], 0, v23
	v_add_u32_e32 v23, 1, v21
	s_nop 0
	v_cndmask_b32_e64 v22, v21, v22, s[0:1]
	v_fma_f32 v21, -v23, v21, v9
	v_cmp_lt_f32_e64 s[0:1], 0, v21
	s_nop 1
	v_cndmask_b32_e64 v21, v22, v23, s[0:1]
	v_mul_f32_e32 v22, 0x37800000, v21
	v_cndmask_b32_e32 v21, v21, v22, vcc
	v_cmp_class_f32_e32 vcc, v9, v149
	s_mov_b32 s0, 0x188b3000
	s_nop 0
	v_cndmask_b32_e32 v21, v21, v9, vcc
	v_pk_mul_f32 v[16:17], v[20:21], v[16:17]
	v_add_co_u32_e32 v20, vcc, s0, v10
	v_pk_fma_f32 v[14:15], v[14:15], v[18:19], v[16:17]
	v_and_b32_sdwa v18, v13, v154 dst_sel:DWORD dst_unused:UNUSED_PAD src0_sel:WORD_1 src1_sel:DWORD
	v_and_b32_sdwa v16, v12, v154 dst_sel:DWORD dst_unused:UNUSED_PAD src0_sel:WORD_1 src1_sel:DWORD
	v_and_b32_sdwa v17, v15, v154 dst_sel:DWORD dst_unused:UNUSED_PAD src0_sel:WORD_1 src1_sel:DWORD
	v_add3_u32 v18, v13, v18, s33
	v_and_b32_sdwa v9, v14, v154 dst_sel:DWORD dst_unused:UNUSED_PAD src0_sel:WORD_1 src1_sel:DWORD
	v_add3_u32 v16, v12, v16, s33
	v_add3_u32 v17, v15, v17, s33
	v_and_b32_e32 v18, 0xffff0000, v18
	v_addc_co_u32_e32 v21, vcc, 0, v11, vcc
	s_mov_b32 s0, 0x188b4000
	v_add3_u32 v9, v14, v9, s33
	v_and_b32_e32 v17, 0xffff0000, v17
	v_or_b32_sdwa v16, v18, v16 dst_sel:DWORD dst_unused:UNUSED_PAD src0_sel:DWORD src1_sel:WORD_1
	v_add_co_u32_e32 v18, vcc, s0, v10
	v_or_b32_sdwa v17, v17, v9 dst_sel:DWORD dst_unused:UNUSED_PAD src0_sel:DWORD src1_sel:WORD_1
	s_nop 0
	v_addc_co_u32_e32 v19, vcc, 0, v11, vcc
	global_store_dwordx2 v[18:19], v[16:17], off offset:-4096
	s_waitcnt vmcnt(10)
	v_mov_b32_e32 v0, v104
	v_mov_b32_e32 v1, v105
	s_nop 0
	s_waitcnt vmcnt(9)
	v_mov_b32_e32 v2, v106
	v_mov_b32_e32 v3, v107
	s_nop 0
	v_lshlrev_b32_e32 v22, 16, v0
	s_nop 0
	v_and_b32_e32 v17, 0xffff0000, v2
	v_lshlrev_b32_e32 v16, 16, v2
	v_mul_f32_e32 v2, 0x3fb8aa3b, v22
	v_exp_f32_e32 v22, v2
	v_and_b32_e32 v9, 0xffff0000, v0
	v_and_b32_e32 v26, 0xffff0000, v1
	v_lshlrev_b32_e32 v1, 16, v1
	v_fma_f32 v2, -v22, v22, 1.0
	v_max_f32_e32 v2, 0, v2
	v_cmp_gt_f32_e32 vcc, s97, v2
	v_mul_f32_e32 v23, 0x4f800000, v2
	v_mul_f32_e32 v1, 0x3fb8aa3b, v1
	v_cndmask_b32_e32 v2, v2, v23, vcc
	v_sqrt_f32_e32 v23, v2
	v_lshlrev_b32_e32 v0, 16, v3
	v_add_u32_e32 v24, -1, v23
	v_fma_f32 v25, -v24, v23, v2
	v_cmp_ge_f32_e64 s[0:1], 0, v25
	v_add_u32_e32 v25, 1, v23
	s_nop 0
	v_cndmask_b32_e64 v24, v23, v24, s[0:1]
	v_fma_f32 v23, -v25, v23, v2
	v_cmp_lt_f32_e64 s[0:1], 0, v23
	s_nop 1
	v_cndmask_b32_e64 v23, v24, v25, s[0:1]
	v_mul_f32_e32 v24, 0x37800000, v23
	v_cndmask_b32_e32 v23, v23, v24, vcc
	v_cmp_class_f32_e32 vcc, v2, v149
	s_nop 1
	v_cndmask_b32_e32 v24, v23, v2, vcc
	v_mul_f32_e32 v2, 0x3fb8aa3b, v9
	v_exp_f32_e32 v23, v2
	s_nop 0
	v_fma_f32 v2, -v23, v23, 1.0
	v_max_f32_e32 v2, 0, v2
	v_cmp_gt_f32_e32 vcc, s97, v2
	v_mul_f32_e32 v9, 0x4f800000, v2
	s_nop 0
	v_cndmask_b32_e32 v2, v2, v9, vcc
	v_sqrt_f32_e32 v9, v2
	s_nop 0
	v_add_u32_e32 v25, -1, v9
	v_fma_f32 v27, -v25, v9, v2
	v_cmp_ge_f32_e64 s[0:1], 0, v27
	v_add_u32_e32 v27, 1, v9
	s_nop 0
	v_cndmask_b32_e64 v25, v9, v25, s[0:1]
	v_fma_f32 v9, -v27, v9, v2
	v_cmp_lt_f32_e64 s[0:1], 0, v9
	s_nop 1
	v_cndmask_b32_e64 v9, v25, v27, s[0:1]
	v_mul_f32_e32 v25, 0x37800000, v9
	v_cndmask_b32_e32 v9, v9, v25, vcc
	v_cmp_class_f32_e32 vcc, v2, v149
	s_nop 1
	v_cndmask_b32_e32 v25, v9, v2, vcc
	v_pk_mul_f32 v[16:17], v[24:25], v[16:17]
	s_nop 0
	v_pk_fma_f32 v[12:13], v[12:13], v[22:23], v[16:17]
	v_exp_f32_e32 v16, v1
	s_nop 0
	v_fma_f32 v1, -v16, v16, 1.0
	v_max_f32_e32 v1, 0, v1
	v_cmp_gt_f32_e32 vcc, s97, v1
	v_mul_f32_e32 v2, 0x4f800000, v1
	s_nop 0
	v_cndmask_b32_e32 v1, v1, v2, vcc
	v_sqrt_f32_e32 v2, v1
	s_nop 0
	v_add_u32_e32 v9, -1, v2
	v_fma_f32 v17, -v9, v2, v1
	v_cmp_ge_f32_e64 s[0:1], 0, v17
	v_add_u32_e32 v17, 1, v2
	s_nop 0
	v_cndmask_b32_e64 v9, v2, v9, s[0:1]
	v_fma_f32 v2, -v17, v2, v1
	v_cmp_lt_f32_e64 s[0:1], 0, v2
	s_nop 1
	v_cndmask_b32_e64 v2, v9, v17, s[0:1]
	v_mul_f32_e32 v9, 0x37800000, v2
	v_cndmask_b32_e32 v2, v2, v9, vcc
	v_cmp_class_f32_e32 vcc, v1, v149
	s_nop 1
	v_cndmask_b32_e32 v2, v2, v1, vcc
	v_mul_f32_e32 v1, 0x3fb8aa3b, v26
	v_exp_f32_e32 v17, v1
	v_and_b32_e32 v1, 0xffff0000, v3
	v_fma_f32 v3, -v17, v17, 1.0
	v_max_f32_e32 v3, 0, v3
	v_cmp_gt_f32_e32 vcc, s97, v3
	v_mul_f32_e32 v9, 0x4f800000, v3
	s_nop 0
	v_cndmask_b32_e32 v3, v3, v9, vcc
	v_sqrt_f32_e32 v9, v3
	s_nop 0
	v_add_u32_e32 v22, -1, v9
	v_fma_f32 v23, -v22, v9, v3
	v_cmp_ge_f32_e64 s[0:1], 0, v23
	v_add_u32_e32 v23, 1, v9
	s_nop 0
	v_cndmask_b32_e64 v22, v9, v22, s[0:1]
	v_fma_f32 v9, -v23, v9, v3
	v_cmp_lt_f32_e64 s[0:1], 0, v9
	s_nop 1
	v_cndmask_b32_e64 v9, v22, v23, s[0:1]
	v_mul_f32_e32 v22, 0x37800000, v9
	v_cndmask_b32_e32 v9, v9, v22, vcc
	v_cmp_class_f32_e32 vcc, v3, v149
	s_nop 1
	v_cndmask_b32_e32 v3, v9, v3, vcc
	v_pk_mul_f32 v[0:1], v[2:3], v[0:1]
	v_and_b32_sdwa v3, v12, v154 dst_sel:DWORD dst_unused:UNUSED_PAD src0_sel:WORD_1 src1_sel:DWORD
	v_pk_fma_f32 v[0:1], v[14:15], v[16:17], v[0:1]
	v_add3_u32 v9, v12, v3, s33
	v_and_b32_sdwa v3, v1, v154 dst_sel:DWORD dst_unused:UNUSED_PAD src0_sel:WORD_1 src1_sel:DWORD
	v_and_b32_sdwa v14, v13, v154 dst_sel:DWORD dst_unused:UNUSED_PAD src0_sel:WORD_1 src1_sel:DWORD
	v_and_b32_sdwa v2, v0, v154 dst_sel:DWORD dst_unused:UNUSED_PAD src0_sel:WORD_1 src1_sel:DWORD
	v_add3_u32 v3, v1, v3, s33
	v_add3_u32 v14, v13, v14, s33
	v_add3_u32 v2, v0, v2, s33
	v_and_b32_e32 v3, 0xffff0000, v3
	v_and_b32_e32 v14, 0xffff0000, v14
	v_or_b32_sdwa v3, v3, v2 dst_sel:DWORD dst_unused:UNUSED_PAD src0_sel:DWORD src1_sel:WORD_1
	v_or_b32_sdwa v2, v14, v9 dst_sel:DWORD dst_unused:UNUSED_PAD src0_sel:DWORD src1_sel:WORD_1
	global_store_dwordx2 v[20:21], v[2:3], off offset:2048
	v_add_co_u32_e32 v2, vcc, s10, v10
	s_nop 1
	v_addc_co_u32_e32 v3, vcc, 0, v11, vcc
	v_add_co_u32_e32 v10, vcc, s11, v10
	s_waitcnt vmcnt(9)
	v_mov_b32_e32 v14, v108
	v_mov_b32_e32 v15, v109
	s_nop 0
	v_addc_co_u32_e32 v11, vcc, 0, v11, vcc
	s_waitcnt vmcnt(8)
	v_mov_b32_e32 v16, v110
	v_mov_b32_e32 v17, v111
	s_nop 0
	v_lshlrev_b32_e32 v22, 16, v14
	v_and_b32_e32 v9, 0xffff0000, v14
	v_mul_f32_e32 v9, 0x3fb8aa3b, v9
	s_nop 0
	v_and_b32_e32 v21, 0xffff0000, v16
	v_lshlrev_b32_e32 v20, 16, v16
	v_mul_f32_e32 v16, 0x3fb8aa3b, v22
	v_exp_f32_e32 v22, v16
	v_and_b32_e32 v26, 0xffff0000, v15
	v_lshlrev_b32_e32 v15, 16, v15
	v_lshlrev_b32_e32 v14, 16, v17
	v_fma_f32 v16, -v22, v22, 1.0
	v_max_f32_e32 v16, 0, v16
	v_cmp_gt_f32_e32 vcc, s97, v16
	v_mul_f32_e32 v23, 0x4f800000, v16
	s_nop 0
	v_cndmask_b32_e32 v16, v16, v23, vcc
	v_sqrt_f32_e32 v23, v16
	s_nop 0
	v_add_u32_e32 v24, -1, v23
	v_fma_f32 v25, -v24, v23, v16
	v_cmp_ge_f32_e64 s[0:1], 0, v25
	v_add_u32_e32 v25, 1, v23
	s_nop 0
	v_cndmask_b32_e64 v24, v23, v24, s[0:1]
	v_fma_f32 v23, -v25, v23, v16
	v_cmp_lt_f32_e64 s[0:1], 0, v23
	s_nop 1
	v_cndmask_b32_e64 v23, v24, v25, s[0:1]
	v_mul_f32_e32 v24, 0x37800000, v23
	v_cndmask_b32_e32 v23, v23, v24, vcc
	v_cmp_class_f32_e32 vcc, v16, v149
	s_nop 1
	v_cndmask_b32_e32 v24, v23, v16, vcc
	v_exp_f32_e32 v23, v9
	s_nop 0
	v_fma_f32 v9, -v23, v23, 1.0
	v_max_f32_e32 v9, 0, v9
	v_cmp_gt_f32_e32 vcc, s97, v9
	v_mul_f32_e32 v16, 0x4f800000, v9
	s_nop 0
	v_cndmask_b32_e32 v9, v9, v16, vcc
	v_sqrt_f32_e32 v16, v9
	s_nop 0
	v_add_u32_e32 v25, -1, v16
	v_fma_f32 v27, -v25, v16, v9
	v_cmp_ge_f32_e64 s[0:1], 0, v27
	v_add_u32_e32 v27, 1, v16
	s_nop 0
	v_cndmask_b32_e64 v25, v16, v25, s[0:1]
	v_fma_f32 v16, -v27, v16, v9
	v_cmp_lt_f32_e64 s[0:1], 0, v16
	s_nop 1
	v_cndmask_b32_e64 v16, v25, v27, s[0:1]
	v_mul_f32_e32 v25, 0x37800000, v16
	v_cndmask_b32_e32 v16, v16, v25, vcc
	v_cmp_class_f32_e32 vcc, v9, v149
	s_nop 1
	v_cndmask_b32_e32 v25, v16, v9, vcc
	v_pk_mul_f32 v[20:21], v[24:25], v[20:21]
	v_mul_f32_e32 v9, 0x3fb8aa3b, v15
	v_pk_fma_f32 v[12:13], v[12:13], v[22:23], v[20:21]
	v_exp_f32_e32 v20, v9
	s_nop 0
	v_fma_f32 v9, -v20, v20, 1.0
	v_max_f32_e32 v9, 0, v9
	v_cmp_gt_f32_e32 vcc, s97, v9
	v_mul_f32_e32 v15, 0x4f800000, v9
	s_nop 0
	v_cndmask_b32_e32 v9, v9, v15, vcc
	v_sqrt_f32_e32 v15, v9
	s_nop 0
	v_add_u32_e32 v16, -1, v15
	v_fma_f32 v21, -v16, v15, v9
	v_cmp_ge_f32_e64 s[0:1], 0, v21
	v_add_u32_e32 v21, 1, v15
	s_nop 0
	v_cndmask_b32_e64 v16, v15, v16, s[0:1]
	v_fma_f32 v15, -v21, v15, v9
	v_cmp_lt_f32_e64 s[0:1], 0, v15
	s_nop 1
	v_cndmask_b32_e64 v15, v16, v21, s[0:1]
	v_mul_f32_e32 v16, 0x37800000, v15
	v_cndmask_b32_e32 v15, v15, v16, vcc
	v_cmp_class_f32_e32 vcc, v9, v149
	s_nop 1
	v_cndmask_b32_e32 v16, v15, v9, vcc
	v_mul_f32_e32 v9, 0x3fb8aa3b, v26
	v_exp_f32_e32 v21, v9
	v_and_b32_e32 v15, 0xffff0000, v17
	v_fma_f32 v9, -v21, v21, 1.0
	v_max_f32_e32 v9, 0, v9
	v_cmp_gt_f32_e32 vcc, s97, v9
	v_mul_f32_e32 v17, 0x4f800000, v9
	s_nop 0
	v_cndmask_b32_e32 v9, v9, v17, vcc
	v_sqrt_f32_e32 v17, v9
	s_nop 0
	v_add_u32_e32 v22, -1, v17
	v_fma_f32 v23, -v22, v17, v9
	v_cmp_ge_f32_e64 s[0:1], 0, v23
	v_add_u32_e32 v23, 1, v17
	s_nop 0
	v_cndmask_b32_e64 v22, v17, v22, s[0:1]
	v_fma_f32 v17, -v23, v17, v9
	v_cmp_lt_f32_e64 s[0:1], 0, v17
	s_nop 1
	v_cndmask_b32_e64 v17, v22, v23, s[0:1]
	v_mul_f32_e32 v22, 0x37800000, v17
	v_cndmask_b32_e32 v17, v17, v22, vcc
	v_cmp_class_f32_e32 vcc, v9, v149
	s_nop 1
	v_cndmask_b32_e32 v17, v17, v9, vcc
	v_pk_mul_f32 v[14:15], v[16:17], v[14:15]
	v_and_b32_sdwa v16, v13, v154 dst_sel:DWORD dst_unused:UNUSED_PAD src0_sel:WORD_1 src1_sel:DWORD
	v_pk_fma_f32 v[14:15], v[0:1], v[20:21], v[14:15]
	v_and_b32_sdwa v1, v12, v154 dst_sel:DWORD dst_unused:UNUSED_PAD src0_sel:WORD_1 src1_sel:DWORD
	v_add3_u32 v9, v12, v1, s33
	v_and_b32_sdwa v1, v15, v154 dst_sel:DWORD dst_unused:UNUSED_PAD src0_sel:WORD_1 src1_sel:DWORD
	v_and_b32_sdwa v0, v14, v154 dst_sel:DWORD dst_unused:UNUSED_PAD src0_sel:WORD_1 src1_sel:DWORD
	v_add3_u32 v1, v15, v1, s33
	v_add3_u32 v16, v13, v16, s33
	v_add3_u32 v0, v14, v0, s33
	v_and_b32_e32 v1, 0xffff0000, v1
	v_and_b32_e32 v16, 0xffff0000, v16
	v_or_b32_sdwa v1, v1, v0 dst_sel:DWORD dst_unused:UNUSED_PAD src0_sel:DWORD src1_sel:WORD_1
	v_or_b32_sdwa v0, v16, v9 dst_sel:DWORD dst_unused:UNUSED_PAD src0_sel:DWORD src1_sel:WORD_1
	global_store_dwordx2 v[18:19], v[0:1], off
	s_waitcnt vmcnt(8)
	v_mov_b32_e32 v0, v210
	v_mov_b32_e32 v1, v211
	s_nop 0
	s_waitcnt vmcnt(7)
	v_mov_b32_e32 v2, v212
	v_mov_b32_e32 v3, v213
	s_nop 0
	v_and_b32_e32 v9, 0xffff0000, v0
	v_lshlrev_b32_e32 v0, 16, v0
	v_mul_f32_e32 v0, 0x3fb8aa3b, v0
	v_exp_f32_e32 v0, v0
	v_and_b32_e32 v20, 0xffff0000, v1
	v_lshlrev_b32_e32 v21, 16, v1
	s_nop 0
	v_and_b32_e32 v11, 0xffff0000, v2
	v_fma_f32 v1, -v0, v0, 1.0
	v_max_f32_e32 v1, 0, v1
	v_cmp_gt_f32_e32 vcc, s97, v1
	v_mul_f32_e32 v16, 0x4f800000, v1
	v_lshlrev_b32_e32 v10, 16, v2
	v_cndmask_b32_e32 v1, v1, v16, vcc
	v_sqrt_f32_e32 v16, v1
	v_lshlrev_b32_e32 v2, 16, v3
	v_and_b32_e32 v3, 0xffff0000, v3
	v_add_u32_e32 v17, -1, v16
	v_fma_f32 v22, -v17, v16, v1
	v_cmp_ge_f32_e64 s[0:1], 0, v22
	v_add_u32_e32 v22, 1, v16
	s_nop 0
	v_cndmask_b32_e64 v17, v16, v17, s[0:1]
	v_fma_f32 v16, -v22, v16, v1
	v_cmp_lt_f32_e64 s[0:1], 0, v16
	s_nop 1
	v_cndmask_b32_e64 v16, v17, v22, s[0:1]
	v_mul_f32_e32 v17, 0x37800000, v16
	v_cndmask_b32_e32 v16, v16, v17, vcc
	v_cmp_class_f32_e32 vcc, v1, v149
	s_nop 1
	v_cndmask_b32_e32 v16, v16, v1, vcc
	v_mul_f32_e32 v1, 0x3fb8aa3b, v9
	v_exp_f32_e32 v1, v1
	s_nop 0
	v_fma_f32 v9, -v1, v1, 1.0
	v_max_f32_e32 v9, 0, v9
	v_cmp_gt_f32_e32 vcc, s97, v9
	v_mul_f32_e32 v17, 0x4f800000, v9
	s_nop 0
	v_cndmask_b32_e32 v9, v9, v17, vcc
	v_sqrt_f32_e32 v17, v9
	s_nop 0
	v_add_u32_e32 v22, -1, v17
	v_fma_f32 v23, -v22, v17, v9
	v_cmp_ge_f32_e64 s[0:1], 0, v23
	v_add_u32_e32 v23, 1, v17
	s_nop 0
	v_cndmask_b32_e64 v22, v17, v22, s[0:1]
	v_fma_f32 v17, -v23, v17, v9
	v_cmp_lt_f32_e64 s[0:1], 0, v17
	s_nop 1
	v_cndmask_b32_e64 v17, v22, v23, s[0:1]
	v_mul_f32_e32 v22, 0x37800000, v17
	v_cndmask_b32_e32 v17, v17, v22, vcc
	v_cmp_class_f32_e32 vcc, v9, v149
	s_nop 1
	v_cndmask_b32_e32 v17, v17, v9, vcc
	v_pk_mul_f32 v[10:11], v[16:17], v[10:11]
	v_mul_f32_e32 v9, 0x3fb8aa3b, v21
	v_pk_fma_f32 v[0:1], v[12:13], v[0:1], v[10:11]
	v_exp_f32_e32 v10, v9
	s_nop 0
	v_fma_f32 v9, -v10, v10, 1.0
	v_max_f32_e32 v9, 0, v9
	v_cmp_gt_f32_e32 vcc, s97, v9
	v_mul_f32_e32 v11, 0x4f800000, v9
	s_nop 0
	v_cndmask_b32_e32 v9, v9, v11, vcc
	v_sqrt_f32_e32 v11, v9
	s_nop 0
	v_add_u32_e32 v12, -1, v11
	v_fma_f32 v13, -v12, v11, v9
	v_cmp_ge_f32_e64 s[0:1], 0, v13
	v_add_u32_e32 v13, 1, v11
	s_nop 0
	v_cndmask_b32_e64 v12, v11, v12, s[0:1]
	v_fma_f32 v11, -v13, v11, v9
	v_cmp_lt_f32_e64 s[0:1], 0, v11
	s_nop 1
	v_cndmask_b32_e64 v11, v12, v13, s[0:1]
	v_mul_f32_e32 v12, 0x37800000, v11
	v_cndmask_b32_e32 v11, v11, v12, vcc
	v_cmp_class_f32_e32 vcc, v9, v149
	s_nop 1
	v_cndmask_b32_e32 v12, v11, v9, vcc
	v_mul_f32_e32 v9, 0x3fb8aa3b, v20
	v_exp_f32_e32 v11, v9
	s_nop 0
	v_fma_f32 v9, -v11, v11, 1.0
	v_max_f32_e32 v9, 0, v9
	v_cmp_gt_f32_e32 vcc, s97, v9
	v_mul_f32_e32 v13, 0x4f800000, v9
	s_nop 0
	v_cndmask_b32_e32 v9, v9, v13, vcc
	v_sqrt_f32_e32 v13, v9
	s_nop 0
	v_add_u32_e32 v16, -1, v13
	v_fma_f32 v17, -v16, v13, v9
	v_cmp_ge_f32_e64 s[0:1], 0, v17
	v_add_u32_e32 v17, 1, v13
	s_nop 0
	v_cndmask_b32_e64 v16, v13, v16, s[0:1]
	v_fma_f32 v13, -v17, v13, v9
	v_cmp_lt_f32_e64 s[0:1], 0, v13
	s_nop 1
	v_cndmask_b32_e64 v13, v16, v17, s[0:1]
	v_mul_f32_e32 v16, 0x37800000, v13
	v_cndmask_b32_e32 v13, v13, v16, vcc
	v_cmp_class_f32_e32 vcc, v9, v149
	s_nop 1
	v_cndmask_b32_e32 v13, v13, v9, vcc
	v_pk_mul_f32 v[2:3], v[12:13], v[2:3]
	v_and_b32_sdwa v12, v1, v154 dst_sel:DWORD dst_unused:UNUSED_PAD src0_sel:WORD_1 src1_sel:DWORD
	v_pk_fma_f32 v[2:3], v[14:15], v[10:11], v[2:3]
	v_and_b32_sdwa v10, v0, v154 dst_sel:DWORD dst_unused:UNUSED_PAD src0_sel:WORD_1 src1_sel:DWORD
	v_and_b32_sdwa v11, v3, v154 dst_sel:DWORD dst_unused:UNUSED_PAD src0_sel:WORD_1 src1_sel:DWORD
	v_and_b32_sdwa v9, v2, v154 dst_sel:DWORD dst_unused:UNUSED_PAD src0_sel:WORD_1 src1_sel:DWORD
	v_add3_u32 v11, v3, v11, s33
	v_add3_u32 v12, v1, v12, s33
	v_add3_u32 v10, v0, v10, s33
	v_add3_u32 v9, v2, v9, s33
	v_and_b32_e32 v11, 0xffff0000, v11
	v_and_b32_e32 v12, 0xffff0000, v12
	v_cmp_eq_u32_e32 vcc, s92, v8
	v_or_b32_sdwa v11, v11, v9 dst_sel:DWORD dst_unused:UNUSED_PAD src0_sel:DWORD src1_sel:WORD_1
	v_or_b32_sdwa v10, v12, v10 dst_sel:DWORD dst_unused:UNUSED_PAD src0_sel:DWORD src1_sel:WORD_1
	s_or_b64 s[44:45], vcc, s[44:45]
	global_store_dwordx2 v[18:19], v[10:11], off offset:2048
	s_andn2_b64 exec, exec, s[44:45]
	s_cbranch_execnz .LBB0_254
	s_or_b64 exec, exec, s[44:45]
	v_cmp_ne_u64_e32 vcc, 0, v[4:5]
	s_and_saveexec_b64 s[0:1], vcc
	s_cbranch_execz .LBB0_257
	global_store_dwordx4 v[4:5], v[0:3], off

.LBB0_278:
	v_lshl_add_u64 v[210:211], v[66:67], 0, s[0:1]
	v_add_co_u32_e32 v212, vcc, s8, v210
	s_nop 1
	v_addc_co_u32_e32 v213, vcc, 0, v211, vcc
	global_load_dwordx4 v[214:217], v[212:213], off offset:-4096
	global_load_dwordx4 v[218:221], v[212:213], off
	v_add_co_u32_e32 v222, vcc, s9, v210
	s_nop 1
	v_addc_co_u32_e32 v223, vcc, 0, v211, vcc
	global_load_dwordx4 v[224:227], v[222:223], off
	v_lshl_add_u64 v[222:223], v[68:69], 0, s[0:1]
	global_load_dwordx4 v[228:231], v[222:223], off
	v_lshl_add_u64 v[110:111], v[66:67], 0, s[0:1]
	v_add_co_u32_e32 v190, vcc, s8, v110
	s_nop 1
	v_addc_co_u32_e32 v191, vcc, 0, v111, vcc
	s_waitcnt vmcnt(3)
	v_mov_b32_e32 v102, v214
	v_mov_b32_e32 v103, v215
	v_mov_b32_e32 v104, v216
	v_mov_b32_e32 v105, v217
	ds_read_b128 v[106:109], v95
	ds_read_b128 v[156:159], v95 offset:4352
	ds_read_b128 v[166:169], v95 offset:8704
	ds_read_b128 v[186:189], v95 offset:13056
	s_setprio 1
	s_waitcnt lgkmcnt(3)
	v_mfma_f32_16x16x32_bf16 v[60:63], v[106:109], v[102:105], v[60:63]
	s_waitcnt lgkmcnt(2)
	v_mfma_f32_16x16x32_bf16 v[44:47], v[156:159], v[102:105], v[44:47]
	s_waitcnt lgkmcnt(1)
	v_mfma_f32_16x16x32_bf16 v[28:31], v[166:169], v[102:105], v[28:31]
	s_waitcnt lgkmcnt(0)
	v_mfma_f32_16x16x32_bf16 v[12:15], v[186:189], v[102:105], v[12:15]
	s_setprio 0
	s_waitcnt vmcnt(2)
	v_mov_b32_e32 v102, v218
	v_mov_b32_e32 v103, v219
	v_mov_b32_e32 v104, v220
	v_mov_b32_e32 v105, v221
	s_setprio 1
	s_nop 0
	v_mfma_f32_16x16x32_bf16 v[56:59], v[106:109], v[102:105], v[56:59]
	v_mfma_f32_16x16x32_bf16 v[40:43], v[156:159], v[102:105], v[40:43]
	v_mfma_f32_16x16x32_bf16 v[24:27], v[166:169], v[102:105], v[24:27]
	v_mfma_f32_16x16x32_bf16 v[8:11], v[186:189], v[102:105], v[8:11]
	s_setprio 0
	v_add_co_u32_e32 v102, vcc, s9, v110
	s_nop 1
	v_addc_co_u32_e32 v103, vcc, 0, v111, vcc
	s_waitcnt vmcnt(1)
	v_mov_b32_e32 v102, v224
	v_mov_b32_e32 v103, v225
	v_mov_b32_e32 v104, v226
	v_mov_b32_e32 v105, v227
	s_setprio 1
	s_nop 0
	v_mfma_f32_16x16x32_bf16 v[52:55], v[106:109], v[102:105], v[52:55]
	v_mfma_f32_16x16x32_bf16 v[36:39], v[156:159], v[102:105], v[36:39]
	v_mfma_f32_16x16x32_bf16 v[20:23], v[166:169], v[102:105], v[20:23]
	v_mfma_f32_16x16x32_bf16 v[4:7], v[186:189], v[102:105], v[4:7]
	s_setprio 0
	v_lshl_add_u64 v[102:103], v[68:69], 0, s[0:1]
	s_waitcnt vmcnt(0)
	v_mov_b32_e32 v102, v228
	v_mov_b32_e32 v103, v229
	v_mov_b32_e32 v104, v230
	v_mov_b32_e32 v105, v231
	s_setprio 1
	s_nop 0
	v_mfma_f32_16x16x32_bf16 v[48:51], v[106:109], v[102:105], v[48:51]
	v_mfma_f32_16x16x32_bf16 v[32:35], v[156:159], v[102:105], v[32:35]
	v_mfma_f32_16x16x32_bf16 v[16:19], v[166:169], v[102:105], v[16:19]
	v_mfma_f32_16x16x32_bf16 v[0:3], v[186:189], v[102:105], v[0:3]
	s_setprio 0
	s_add_u32 s0, s0, 64
	s_addc_u32 s1, s1, 0
	s_cmpk_eq_i32 s0, 0x100
	v_add_u32_e32 v95, 64, v95
	s_cbranch_scc0 .LBB0_278
	s_lshl_b32 s44, s94, 8
	v_lshl_add_u64 v[102:103], v[88:89], 0, s[2:3]
	s_mov_b32 s2, 0
	s_mov_b64 s[0:1], -1
	s_movk_i32 s8, 0x3200
	s_mov_b32 s9, 0x5040100
.LBB0_280:
	v_cndmask_b32_e64 v95, 0, 1, s[0:1]
	s_lshl_b32 s0, s2, 6
	v_cmp_ne_u32_e32 vcc, 1, v95
	v_add3_u32 v95, v78, s0, v124
	ds_read_b128 v[104:107], v95 offset:40960
	ds_read_b128 v[108:111], v95 offset:43264
	ds_read_b128 v[156:159], v95 offset:45568
	ds_read_b128 v[166:169], v95 offset:47872
	v_lshl_or_b32 v95, s2, 5, v123
	v_or_b32_e32 v188, 3, v95
	v_or_b32_e32 v189, 5, v95
	v_min_i32_e32 v188, s93, v188
	v_min_i32_e32 v189, s93, v189
	v_add_u32_e32 v188, s7, v188
	v_add_u32_e32 v189, s7, v189
	v_min_i32_e32 v101, s93, v95
	v_or_b32_e32 v186, 1, v95
	v_or_b32_e32 v187, 2, v95
	v_mad_i64_i32 v[196:197], s[0:1], v188, s8, v[102:103]
	v_or_b32_e32 v188, 4, v95
	v_mad_i64_i32 v[200:201], s[0:1], v189, s8, v[102:103]
	v_or_b32_e32 v189, 6, v95
	v_or_b32_e32 v95, 7, v95
	v_min_i32_e32 v186, s93, v186
	v_min_i32_e32 v187, s93, v187
	v_min_i32_e32 v188, s93, v188
	v_min_i32_e32 v189, s93, v189
	v_min_i32_e32 v95, s93, v95
	v_add_u32_e32 v101, s7, v101
	v_add_u32_e32 v186, s7, v186
	v_add_u32_e32 v187, s7, v187
	v_add_u32_e32 v188, s7, v188
	v_add_u32_e32 v189, s7, v189
	v_add_u32_e32 v95, s7, v95
	v_mad_i64_i32 v[190:191], s[0:1], v101, s8, v[102:103]
	v_mad_i64_i32 v[192:193], s[0:1], v186, s8, v[102:103]
	v_mad_i64_i32 v[194:195], s[0:1], v187, s8, v[102:103]
	v_mad_i64_i32 v[198:199], s[0:1], v188, s8, v[102:103]
	v_mad_i64_i32 v[202:203], s[0:1], v189, s8, v[102:103]
	v_mad_i64_i32 v[206:207], s[0:1], v95, s8, v[102:103]
	global_load_ushort v101, v[190:191], off offset:2048
	global_load_ushort v186, v[192:193], off offset:2048
	global_load_ushort v187, v[194:195], off offset:2048
	global_load_ushort v204, v[196:197], off offset:2048
	global_load_ushort v188, v[198:199], off offset:2048
	global_load_ushort v208, v[200:201], off offset:2048
	global_load_ushort v189, v[202:203], off offset:2048
	global_load_ushort v95, v[206:207], off offset:2048
	global_load_ushort v210, v[190:191], off offset:2080
	global_load_ushort v211, v[192:193], off offset:2080
	global_load_ushort v212, v[194:195], off offset:2080
	global_load_ushort v213, v[196:197], off offset:2080
	global_load_ushort v214, v[198:199], off offset:2080
	global_load_ushort v215, v[200:201], off offset:2080
	global_load_ushort v216, v[202:203], off offset:2080
	global_load_ushort v217, v[206:207], off offset:2080
	global_load_ushort v218, v[190:191], off offset:2112
	global_load_ushort v219, v[192:193], off offset:2112
	global_load_ushort v220, v[194:195], off offset:2112
	global_load_ushort v221, v[196:197], off offset:2112
	global_load_ushort v222, v[198:199], off offset:2112
	global_load_ushort v223, v[200:201], off offset:2112
	global_load_ushort v224, v[202:203], off offset:2112
	global_load_ushort v225, v[206:207], off offset:2112
	global_load_ushort v226, v[190:191], off offset:2144
	global_load_ushort v227, v[192:193], off offset:2144
	global_load_ushort v228, v[194:195], off offset:2144
	global_load_ushort v229, v[196:197], off offset:2144
	global_load_ushort v230, v[198:199], off offset:2144
	global_load_ushort v231, v[200:201], off offset:2144
	global_load_ushort v232, v[202:203], off offset:2144
	global_load_ushort v233, v[206:207], off offset:2144
	s_setprio 1
	s_waitcnt vmcnt(24)
	v_perm_b32 v189, v95, v189, s9
	v_perm_b32 v188, v208, v188, s9
	v_perm_b32 v187, v204, v187, s9
	v_perm_b32 v186, v186, v101, s9
	s_waitcnt lgkmcnt(3)
	s_nop 0
	v_mfma_f32_16x16x32_bf16 v[60:63], v[104:107], v[186:189], v[60:63]
	s_waitcnt lgkmcnt(2)
	v_mfma_f32_16x16x32_bf16 v[44:47], v[108:111], v[186:189], v[44:47]
	s_waitcnt lgkmcnt(1)
	v_mfma_f32_16x16x32_bf16 v[28:31], v[156:159], v[186:189], v[28:31]
	s_waitcnt lgkmcnt(0)
	v_mfma_f32_16x16x32_bf16 v[12:15], v[166:169], v[186:189], v[12:15]
	s_setprio 0
	s_setprio 1
	s_waitcnt vmcnt(16)
	v_perm_b32 v189, v217, v216, s9
	v_perm_b32 v188, v215, v214, s9
	v_perm_b32 v187, v213, v212, s9
	v_perm_b32 v186, v211, v210, s9
	s_nop 1
	v_mfma_f32_16x16x32_bf16 v[56:59], v[104:107], v[186:189], v[56:59]
	v_mfma_f32_16x16x32_bf16 v[40:43], v[108:111], v[186:189], v[40:43]
	v_mfma_f32_16x16x32_bf16 v[24:27], v[156:159], v[186:189], v[24:27]
	v_mfma_f32_16x16x32_bf16 v[8:11], v[166:169], v[186:189], v[8:11]
	s_setprio 0
	s_setprio 1
	s_waitcnt vmcnt(8)
	v_perm_b32 v189, v225, v224, s9
	v_perm_b32 v188, v223, v222, s9
	v_perm_b32 v187, v221, v220, s9
	v_perm_b32 v186, v219, v218, s9
	s_nop 1
	v_mfma_f32_16x16x32_bf16 v[52:55], v[104:107], v[186:189], v[52:55]
	v_mfma_f32_16x16x32_bf16 v[36:39], v[108:111], v[186:189], v[36:39]
	v_mfma_f32_16x16x32_bf16 v[20:23], v[156:159], v[186:189], v[20:23]
	v_mfma_f32_16x16x32_bf16 v[4:7], v[166:169], v[186:189], v[4:7]
	s_setprio 0
	s_nop 0
	s_setprio 1
	s_waitcnt vmcnt(0)
	v_perm_b32 v189, v233, v232, s9
	v_perm_b32 v188, v231, v230, s9
	v_perm_b32 v187, v229, v228, s9
	v_perm_b32 v186, v227, v226, s9
	s_nop 1
	v_mfma_f32_16x16x32_bf16 v[48:51], v[104:107], v[186:189], v[48:51]
	v_mfma_f32_16x16x32_bf16 v[32:35], v[108:111], v[186:189], v[32:35]
	v_mfma_f32_16x16x32_bf16 v[16:19], v[156:159], v[186:189], v[16:19]
	v_mfma_f32_16x16x32_bf16 v[0:3], v[166:169], v[186:189], v[0:3]
	s_setprio 0
	s_mov_b64 s[0:1], 0
	s_mov_b32 s2, 1
	s_cbranch_vccz .LBB0_280
	v_mul_f32_e32 v95, v56, v56
	v_fmac_f32_e32 v95, v60, v60
	v_fmac_f32_e32 v95, v52, v52
	v_fmac_f32_e32 v95, v48, v48
	s_nop 1
	v_add_f32_dpp v95, v95, v95 quad_perm:[1,0,3,2] row_mask:0xf bank_mask:0xf bound_ctrl:1
	s_nop 1
	v_add_f32_dpp v95, v95, v95 quad_perm:[2,3,0,1] row_mask:0xf bank_mask:0xf bound_ctrl:1
	s_nop 1
	v_add_f32_dpp v95, v95, v95 row_half_mirror row_mask:0xf bank_mask:0xf bound_ctrl:1
	s_nop 1
	v_mov_b32_dpp v101, v95 row_mirror row_mask:0xf bank_mask:0xf bound_ctrl:1
	s_and_saveexec_b64 s[0:1], s[40:41]
	v_add_f32_e32 v95, v95, v101
	ds_write_b32 v184, v95 offset:5120
	s_or_b64 exec, exec, s[0:1]
	v_mul_f32_e32 v95, v57, v57
	v_fmac_f32_e32 v95, v61, v61
	v_fmac_f32_e32 v95, v53, v53
	v_fmac_f32_e32 v95, v49, v49
	s_nop 1
	v_add_f32_dpp v95, v95, v95 quad_perm:[1,0,3,2] row_mask:0xf bank_mask:0xf bound_ctrl:1
	s_nop 1
	v_add_f32_dpp v95, v95, v95 quad_perm:[2,3,0,1] row_mask:0xf bank_mask:0xf bound_ctrl:1
	s_nop 1
	v_add_f32_dpp v95, v95, v95 row_half_mirror row_mask:0xf bank_mask:0xf bound_ctrl:1
	s_nop 1
	v_mov_b32_dpp v101, v95 row_mirror row_mask:0xf bank_mask:0xf bound_ctrl:1
	s_and_saveexec_b64 s[0:1], s[40:41]
	v_add_f32_e32 v95, v95, v101
	ds_write_b32 v184, v95 offset:5124
	s_or_b64 exec, exec, s[0:1]
	v_mul_f32_e32 v95, v58, v58
	v_fmac_f32_e32 v95, v62, v62
	v_fmac_f32_e32 v95, v54, v54
	v_fmac_f32_e32 v95, v50, v50
	s_nop 1
	v_add_f32_dpp v95, v95, v95 quad_perm:[1,0,3,2] row_mask:0xf bank_mask:0xf bound_ctrl:1
	s_nop 1
	v_add_f32_dpp v95, v95, v95 quad_perm:[2,3,0,1] row_mask:0xf bank_mask:0xf bound_ctrl:1
	s_nop 1
	v_add_f32_dpp v95, v95, v95 row_half_mirror row_mask:0xf bank_mask:0xf bound_ctrl:1
	s_nop 1
	v_mov_b32_dpp v101, v95 row_mirror row_mask:0xf bank_mask:0xf bound_ctrl:1
	s_and_saveexec_b64 s[0:1], s[40:41]
	v_add_f32_e32 v95, v95, v101
	ds_write_b32 v184, v95 offset:5128
	s_or_b64 exec, exec, s[0:1]
	v_mul_f32_e32 v95, v59, v59
	v_fmac_f32_e32 v95, v63, v63
	v_fmac_f32_e32 v95, v55, v55
	v_fmac_f32_e32 v95, v51, v51
	s_nop 1
	v_add_f32_dpp v95, v95, v95 quad_perm:[1,0,3,2] row_mask:0xf bank_mask:0xf bound_ctrl:1
	s_nop 1
	v_add_f32_dpp v95, v95, v95 quad_perm:[2,3,0,1] row_mask:0xf bank_mask:0xf bound_ctrl:1
	s_nop 1
	v_add_f32_dpp v95, v95, v95 row_half_mirror row_mask:0xf bank_mask:0xf bound_ctrl:1
	s_nop 1
	v_mov_b32_dpp v101, v95 row_mirror row_mask:0xf bank_mask:0xf bound_ctrl:1
	s_and_saveexec_b64 s[0:1], s[40:41]
	v_add_f32_e32 v95, v95, v101
	ds_write_b32 v184, v95 offset:5132
	s_or_b64 exec, exec, s[0:1]
	v_mul_f32_e32 v95, v40, v40
	v_fmac_f32_e32 v95, v44, v44
	v_fmac_f32_e32 v95, v36, v36
	v_fmac_f32_e32 v95, v32, v32
	s_nop 1
	v_add_f32_dpp v95, v95, v95 quad_perm:[1,0,3,2] row_mask:0xf bank_mask:0xf bound_ctrl:1
	s_nop 1
	v_add_f32_dpp v95, v95, v95 quad_perm:[2,3,0,1] row_mask:0xf bank_mask:0xf bound_ctrl:1
	s_nop 1
	v_add_f32_dpp v95, v95, v95 row_half_mirror row_mask:0xf bank_mask:0xf bound_ctrl:1
	s_nop 1
	v_mov_b32_dpp v101, v95 row_mirror row_mask:0xf bank_mask:0xf bound_ctrl:1
	s_and_saveexec_b64 s[0:1], s[40:41]
	v_add_f32_e32 v95, v95, v101
	ds_write_b32 v184, v95 offset:5184
	s_or_b64 exec, exec, s[0:1]
	v_mul_f32_e32 v95, v41, v41
	v_fmac_f32_e32 v95, v45, v45
	v_fmac_f32_e32 v95, v37, v37
	v_fmac_f32_e32 v95, v33, v33
	s_nop 1
	v_add_f32_dpp v95, v95, v95 quad_perm:[1,0,3,2] row_mask:0xf bank_mask:0xf bound_ctrl:1
	s_nop 1
	v_add_f32_dpp v95, v95, v95 quad_perm:[2,3,0,1] row_mask:0xf bank_mask:0xf bound_ctrl:1
	s_nop 1
	v_add_f32_dpp v95, v95, v95 row_half_mirror row_mask:0xf bank_mask:0xf bound_ctrl:1
	s_nop 1
	v_mov_b32_dpp v101, v95 row_mirror row_mask:0xf bank_mask:0xf bound_ctrl:1
	s_and_saveexec_b64 s[0:1], s[40:41]
	v_add_f32_e32 v95, v95, v101
	ds_write_b32 v184, v95 offset:5188
	s_or_b64 exec, exec, s[0:1]
	v_mul_f32_e32 v95, v42, v42
	v_fmac_f32_e32 v95, v46, v46
	v_fmac_f32_e32 v95, v38, v38
	v_fmac_f32_e32 v95, v34, v34
	s_nop 1
	v_add_f32_dpp v95, v95, v95 quad_perm:[1,0,3,2] row_mask:0xf bank_mask:0xf bound_ctrl:1
	s_nop 1
	v_add_f32_dpp v95, v95, v95 quad_perm:[2,3,0,1] row_mask:0xf bank_mask:0xf bound_ctrl:1
	s_nop 1
	v_add_f32_dpp v95, v95, v95 row_half_mirror row_mask:0xf bank_mask:0xf bound_ctrl:1
	s_nop 1
	v_mov_b32_dpp v101, v95 row_mirror row_mask:0xf bank_mask:0xf bound_ctrl:1
	s_and_saveexec_b64 s[0:1], s[40:41]
	v_add_f32_e32 v95, v95, v101
	ds_write_b32 v184, v95 offset:5192
	s_or_b64 exec, exec, s[0:1]
	v_mul_f32_e32 v95, v43, v43
	v_fmac_f32_e32 v95, v47, v47
	v_fmac_f32_e32 v95, v39, v39
	v_fmac_f32_e32 v95, v35, v35
	s_nop 1
	v_add_f32_dpp v95, v95, v95 quad_perm:[1,0,3,2] row_mask:0xf bank_mask:0xf bound_ctrl:1
	s_nop 1
	v_add_f32_dpp v95, v95, v95 quad_perm:[2,3,0,1] row_mask:0xf bank_mask:0xf bound_ctrl:1
	s_nop 1
	v_add_f32_dpp v95, v95, v95 row_half_mirror row_mask:0xf bank_mask:0xf bound_ctrl:1
	s_nop 1
	v_mov_b32_dpp v101, v95 row_mirror row_mask:0xf bank_mask:0xf bound_ctrl:1
	s_and_saveexec_b64 s[0:1], s[40:41]
	v_add_f32_e32 v95, v95, v101
	ds_write_b32 v184, v95 offset:5196
	s_or_b64 exec, exec, s[0:1]
	v_mul_f32_e32 v95, v24, v24
	v_fmac_f32_e32 v95, v28, v28
	v_fmac_f32_e32 v95, v20, v20
	v_fmac_f32_e32 v95, v16, v16
	s_nop 1
	v_add_f32_dpp v95, v95, v95 quad_perm:[1,0,3,2] row_mask:0xf bank_mask:0xf bound_ctrl:1
	s_nop 1
	v_add_f32_dpp v95, v95, v95 quad_perm:[2,3,0,1] row_mask:0xf bank_mask:0xf bound_ctrl:1
	s_nop 1
	v_add_f32_dpp v95, v95, v95 row_half_mirror row_mask:0xf bank_mask:0xf bound_ctrl:1
	s_nop 1
	v_mov_b32_dpp v101, v95 row_mirror row_mask:0xf bank_mask:0xf bound_ctrl:1
	s_and_saveexec_b64 s[0:1], s[40:41]
	v_add_f32_e32 v95, v95, v101
	ds_write_b32 v184, v95 offset:5248
	s_or_b64 exec, exec, s[0:1]
	v_mul_f32_e32 v95, v25, v25
	v_fmac_f32_e32 v95, v29, v29
	v_fmac_f32_e32 v95, v21, v21
	v_fmac_f32_e32 v95, v17, v17
	s_nop 1
	v_add_f32_dpp v95, v95, v95 quad_perm:[1,0,3,2] row_mask:0xf bank_mask:0xf bound_ctrl:1
	s_nop 1
	v_add_f32_dpp v95, v95, v95 quad_perm:[2,3,0,1] row_mask:0xf bank_mask:0xf bound_ctrl:1
	s_nop 1
	v_add_f32_dpp v95, v95, v95 row_half_mirror row_mask:0xf bank_mask:0xf bound_ctrl:1
	s_nop 1
	v_mov_b32_dpp v101, v95 row_mirror row_mask:0xf bank_mask:0xf bound_ctrl:1
	s_and_saveexec_b64 s[0:1], s[40:41]
	v_add_f32_e32 v95, v95, v101
	ds_write_b32 v184, v95 offset:5252
	s_or_b64 exec, exec, s[0:1]
	v_mul_f32_e32 v95, v26, v26
	v_fmac_f32_e32 v95, v30, v30
	v_fmac_f32_e32 v95, v22, v22
	v_fmac_f32_e32 v95, v18, v18
	s_nop 1
	v_add_f32_dpp v95, v95, v95 quad_perm:[1,0,3,2] row_mask:0xf bank_mask:0xf bound_ctrl:1
	s_nop 1
	v_add_f32_dpp v95, v95, v95 quad_perm:[2,3,0,1] row_mask:0xf bank_mask:0xf bound_ctrl:1
	s_nop 1
	v_add_f32_dpp v95, v95, v95 row_half_mirror row_mask:0xf bank_mask:0xf bound_ctrl:1
	s_nop 1
	v_mov_b32_dpp v101, v95 row_mirror row_mask:0xf bank_mask:0xf bound_ctrl:1
	s_and_saveexec_b64 s[0:1], s[40:41]
	v_add_f32_e32 v95, v95, v101
	ds_write_b32 v184, v95 offset:5256
	s_or_b64 exec, exec, s[0:1]
	v_mul_f32_e32 v95, v27, v27
	v_fmac_f32_e32 v95, v31, v31
	v_fmac_f32_e32 v95, v23, v23
	v_fmac_f32_e32 v95, v19, v19
	s_nop 1
	v_add_f32_dpp v95, v95, v95 quad_perm:[1,0,3,2] row_mask:0xf bank_mask:0xf bound_ctrl:1
	s_nop 1
	v_add_f32_dpp v95, v95, v95 quad_perm:[2,3,0,1] row_mask:0xf bank_mask:0xf bound_ctrl:1
	s_nop 1
	v_add_f32_dpp v95, v95, v95 row_half_mirror row_mask:0xf bank_mask:0xf bound_ctrl:1
	s_nop 1
	v_mov_b32_dpp v101, v95 row_mirror row_mask:0xf bank_mask:0xf bound_ctrl:1
	s_and_saveexec_b64 s[0:1], s[40:41]
	v_add_f32_e32 v95, v95, v101
	ds_write_b32 v184, v95 offset:5260
	s_or_b64 exec, exec, s[0:1]
	v_mul_f32_e32 v95, v8, v8
	v_fmac_f32_e32 v95, v12, v12
	v_fmac_f32_e32 v95, v4, v4
	v_fmac_f32_e32 v95, v0, v0
	s_nop 1
	v_add_f32_dpp v95, v95, v95 quad_perm:[1,0,3,2] row_mask:0xf bank_mask:0xf bound_ctrl:1
	s_nop 1
	v_add_f32_dpp v95, v95, v95 quad_perm:[2,3,0,1] row_mask:0xf bank_mask:0xf bound_ctrl:1
	s_nop 1
	v_add_f32_dpp v95, v95, v95 row_half_mirror row_mask:0xf bank_mask:0xf bound_ctrl:1
	s_nop 1
	v_mov_b32_dpp v101, v95 row_mirror row_mask:0xf bank_mask:0xf bound_ctrl:1
	s_and_saveexec_b64 s[0:1], s[40:41]
	v_add_f32_e32 v95, v95, v101
	ds_write_b32 v184, v95 offset:5312
	s_or_b64 exec, exec, s[0:1]
	v_mul_f32_e32 v95, v9, v9
	v_fmac_f32_e32 v95, v13, v13
	v_fmac_f32_e32 v95, v5, v5
	v_fmac_f32_e32 v95, v1, v1
	s_nop 1
	v_add_f32_dpp v95, v95, v95 quad_perm:[1,0,3,2] row_mask:0xf bank_mask:0xf bound_ctrl:1
	s_nop 1
	v_add_f32_dpp v95, v95, v95 quad_perm:[2,3,0,1] row_mask:0xf bank_mask:0xf bound_ctrl:1
	s_nop 1
	v_add_f32_dpp v95, v95, v95 row_half_mirror row_mask:0xf bank_mask:0xf bound_ctrl:1
	s_nop 1
	v_mov_b32_dpp v101, v95 row_mirror row_mask:0xf bank_mask:0xf bound_ctrl:1
	s_and_saveexec_b64 s[0:1], s[40:41]
	v_add_f32_e32 v95, v95, v101
	ds_write_b32 v184, v95 offset:5316
	s_or_b64 exec, exec, s[0:1]
	v_mul_f32_e32 v95, v10, v10
	v_fmac_f32_e32 v95, v14, v14
	v_fmac_f32_e32 v95, v6, v6
	v_fmac_f32_e32 v95, v2, v2
	s_nop 1
	v_add_f32_dpp v95, v95, v95 quad_perm:[1,0,3,2] row_mask:0xf bank_mask:0xf bound_ctrl:1
	s_nop 1
	v_add_f32_dpp v95, v95, v95 quad_perm:[2,3,0,1] row_mask:0xf bank_mask:0xf bound_ctrl:1
	s_nop 1
	v_add_f32_dpp v95, v95, v95 row_half_mirror row_mask:0xf bank_mask:0xf bound_ctrl:1
	s_nop 1
	v_mov_b32_dpp v101, v95 row_mirror row_mask:0xf bank_mask:0xf bound_ctrl:1
	s_and_saveexec_b64 s[0:1], s[40:41]
	v_add_f32_e32 v95, v95, v101
	ds_write_b32 v184, v95 offset:5320
	s_or_b64 exec, exec, s[0:1]
	v_mul_f32_e32 v95, v11, v11
	v_fmac_f32_e32 v95, v15, v15
	v_fmac_f32_e32 v95, v7, v7
	v_fmac_f32_e32 v95, v3, v3
	s_nop 1
	v_add_f32_dpp v95, v95, v95 quad_perm:[1,0,3,2] row_mask:0xf bank_mask:0xf bound_ctrl:1
	s_nop 1
	v_add_f32_dpp v95, v95, v95 quad_perm:[2,3,0,1] row_mask:0xf bank_mask:0xf bound_ctrl:1
	s_nop 1
	v_add_f32_dpp v95, v95, v95 row_half_mirror row_mask:0xf bank_mask:0xf bound_ctrl:1
	s_nop 1
	v_mov_b32_dpp v101, v95 row_mirror row_mask:0xf bank_mask:0xf bound_ctrl:1
	s_and_saveexec_b64 s[0:1], s[40:41]
	v_add_f32_e32 v95, v95, v101
	ds_write_b32 v184, v95 offset:5324
	s_or_b64 exec, exec, s[0:1]
	s_lshl_b32 s0, s44, 2
	v_readlane_b32 s1, v254, 59
	s_add_u32 s0, s1, s0
	v_readlane_b32 s1, v254, 53
	s_addc_u32 s1, s1, 0
	s_waitcnt lgkmcnt(0)
	v_lshl_add_u64 v[104:105], v[82:83], 2, s[0:1]
	s_barrier
	global_load_dword v186, v[104:105], off
	global_load_dword v101, v[104:105], off offset:64
	global_load_dword v95, v[104:105], off offset:128
	v_lshl_add_u64 v[104:105], v[84:85], 2, s[0:1]
	global_load_dword v187, v[104:105], off
	s_lshl_b32 s2, s44, 1
	v_add_u32_e32 v102, s7, v81
	s_add_u32 s44, s66, s2
	v_readlane_b32 s2, v254, 57
	v_ashrrev_i32_e32 v103, 31, v102
	s_addc_u32 s45, s2, 0
	v_lshlrev_b64 v[102:103], 11, v[102:103]
	v_lshl_add_u64 v[106:107], s[44:45], 0, v[102:103]
	v_lshlrev_b64 v[102:103], 1, v[82:83]
	v_lshlrev_b64 v[104:105], 1, v[84:85]
	v_lshl_add_u64 v[110:111], v[106:107], 0, v[102:103]
	v_lshl_add_u64 v[192:193], v[106:107], 0, v[104:105]
	ds_read_b128 v[106:109], v78 offset:5120
	ds_read_b128 v[156:159], v78 offset:5376
	ds_read_b128 v[166:169], v78 offset:5632
	ds_read_b128 v[188:191], v78 offset:5888
	s_mov_b32 s0, 0x358637bd
	s_mov_b32 s8, 0x3b800000
	s_waitcnt lgkmcnt(2)
	v_pk_add_f32 v[106:107], v[106:107], v[156:157]
	s_mov_b32 s2, 0x800000
	s_waitcnt lgkmcnt(1)
	v_pk_add_f32 v[106:107], v[106:107], v[166:167]
	s_waitcnt lgkmcnt(0)
	v_pk_add_f32 v[156:157], v[106:107], v[188:189]
	v_mov_b64_e32 v[106:107], s[0:1]
	v_pk_fma_f32 v[156:157], v[156:157], s[8:9], v[106:107] op_sel_hi:[1,0,0]
	s_nop 0
	v_mul_f32_e32 v166, 0x4b800000, v156
	v_cmp_gt_f32_e64 s[0:1], s2, v156
	v_cmp_gt_f32_e32 vcc, s2, v157
	s_nop 0
	v_cndmask_b32_e64 v156, v156, v166, s[0:1]
	v_rsq_f32_e32 v156, v156
	s_nop 0
	v_mul_f32_e32 v166, 0x45800000, v156
	v_cndmask_b32_e64 v156, v156, v166, s[0:1]
	v_mul_f32_e32 v60, v60, v156
	v_mul_f32_e32 v56, v56, v156
	v_mul_f32_e32 v52, v52, v156
	v_mul_f32_e32 v48, v48, v156
	s_waitcnt vmcnt(2)
	v_mul_f32_e32 v56, v101, v56
	v_mul_f32_e32 v60, v186, v60
	v_bfe_u32 v166, v60, 16, 1
	v_add3_u32 v60, v60, v166, s33
	global_store_short_d16_hi v[110:111], v60, off
	v_bfe_u32 v60, v56, 16, 1
	v_add3_u32 v56, v56, v60, s33
	s_waitcnt vmcnt(2)
	v_mul_f32_e32 v52, v95, v52
	global_store_short_d16_hi v[110:111], v56, off offset:32
	v_bfe_u32 v56, v52, 16, 1
	v_add3_u32 v52, v52, v56, s33
	s_waitcnt vmcnt(2)
	v_mul_f32_e32 v48, v187, v48
	global_store_short_d16_hi v[110:111], v52, off offset:64
	v_bfe_u32 v52, v48, 16, 1
	v_add3_u32 v48, v48, v52, s33
	global_store_short_d16_hi v[192:193], v48, off
	v_mul_f32_e32 v48, 0x4b800000, v157
	v_cndmask_b32_e32 v48, v157, v48, vcc
	v_rsq_f32_e32 v48, v48
	v_add_u32_e32 v110, s7, v125
	v_ashrrev_i32_e32 v111, 31, v110
	v_lshlrev_b64 v[110:111], 11, v[110:111]
	v_mul_f32_e32 v52, 0x45800000, v48
	v_cndmask_b32_e32 v48, v48, v52, vcc
	v_mul_f32_e32 v52, v61, v48
	v_mul_f32_e32 v52, v186, v52
	v_lshl_add_u64 v[110:111], s[44:45], 0, v[110:111]
	v_bfe_u32 v56, v52, 16, 1
	v_add3_u32 v52, v52, v56, s33
	v_lshl_add_u64 v[60:61], v[110:111], 0, v[102:103]
	global_store_short_d16_hi v[60:61], v52, off
	v_mul_f32_e32 v52, v57, v48
	v_mul_f32_e32 v52, v101, v52
	v_bfe_u32 v56, v52, 16, 1
	v_add3_u32 v52, v52, v56, s33
	global_store_short_d16_hi v[60:61], v52, off offset:32
	v_mul_f32_e32 v52, v53, v48
	v_pk_add_f32 v[56:57], v[108:109], v[158:159]
	v_mul_f32_e32 v52, v95, v52
	v_pk_add_f32 v[56:57], v[56:57], v[168:169]
	v_bfe_u32 v53, v52, 16, 1
	v_pk_add_f32 v[56:57], v[56:57], v[190:191]
	v_add3_u32 v52, v52, v53, s33
	v_pk_fma_f32 v[56:57], v[56:57], s[8:9], v[106:107] op_sel_hi:[1,0,0]
	global_store_short_d16_hi v[60:61], v52, off offset:64
	v_mul_f32_e32 v60, 0x4b800000, v56
	v_cmp_gt_f32_e64 s[0:1], s2, v56
	v_mul_f32_e32 v48, v49, v48
	v_mul_f32_e32 v48, v187, v48
	v_cndmask_b32_e64 v56, v56, v60, s[0:1]
	v_rsq_f32_e32 v56, v56
	v_bfe_u32 v49, v48, 16, 1
	v_add3_u32 v52, v48, v49, s33
	v_lshl_add_u64 v[48:49], v[110:111], 0, v[104:105]
	v_mul_f32_e32 v60, 0x45800000, v56
	global_store_short_d16_hi v[48:49], v52, off
	v_add_u32_e32 v48, s7, v126
	v_cndmask_b32_e64 v56, v56, v60, s[0:1]
	v_ashrrev_i32_e32 v49, 31, v48
	v_mul_f32_e32 v60, v62, v56
	v_lshlrev_b64 v[48:49], 11, v[48:49]
	v_mul_f32_e32 v60, v186, v60
	v_lshl_add_u64 v[48:49], s[44:45], 0, v[48:49]
	v_bfe_u32 v61, v60, 16, 1
	v_mul_f32_e32 v58, v58, v56
	v_lshl_add_u64 v[52:53], v[48:49], 0, v[102:103]
	v_add3_u32 v60, v60, v61, s33
	v_mul_f32_e32 v58, v101, v58
	global_store_short_d16_hi v[52:53], v60, off
	v_bfe_u32 v60, v58, 16, 1
	v_mul_f32_e32 v54, v54, v56
	v_add3_u32 v58, v58, v60, s33
	v_mul_f32_e32 v54, v95, v54
	global_store_short_d16_hi v[52:53], v58, off offset:32
	v_bfe_u32 v58, v54, 16, 1
	v_mul_f32_e32 v50, v50, v56
	v_add3_u32 v54, v54, v58, s33
	v_mul_f32_e32 v50, v187, v50
	global_store_short_d16_hi v[52:53], v54, off offset:64
	v_bfe_u32 v52, v50, 16, 1
	v_lshl_add_u64 v[48:49], v[48:49], 0, v[104:105]
	v_add3_u32 v50, v50, v52, s33
	v_cmp_gt_f32_e32 vcc, s2, v57
	global_store_short_d16_hi v[48:49], v50, off
	v_mul_f32_e32 v48, 0x4b800000, v57
	v_cndmask_b32_e32 v48, v57, v48, vcc
	v_rsq_f32_e32 v48, v48
	s_nop 0
	v_mul_f32_e32 v49, 0x45800000, v48
	v_cndmask_b32_e32 v50, v48, v49, vcc
	v_add_u32_e32 v48, s7, v127
	v_ashrrev_i32_e32 v49, 31, v48
	v_mul_f32_e32 v52, v63, v50
	v_lshlrev_b64 v[48:49], 11, v[48:49]
	v_mul_f32_e32 v52, v186, v52
	v_lshl_add_u64 v[48:49], s[44:45], 0, v[48:49]
	v_bfe_u32 v53, v52, 16, 1
	v_add3_u32 v54, v52, v53, s33
	v_lshl_add_u64 v[52:53], v[48:49], 0, v[102:103]
	global_store_short_d16_hi v[52:53], v54, off
	v_mul_f32_e32 v54, v59, v50
	v_mul_f32_e32 v54, v101, v54
	v_bfe_u32 v56, v54, 16, 1
	v_add3_u32 v54, v54, v56, s33
	global_store_short_d16_hi v[52:53], v54, off offset:32
	v_mul_f32_e32 v54, v55, v50
	v_mul_f32_e32 v50, v51, v50
	v_mul_f32_e32 v54, v95, v54
	v_mul_f32_e32 v50, v187, v50
	v_bfe_u32 v55, v54, 16, 1
	v_bfe_u32 v51, v50, 16, 1
	v_add3_u32 v54, v54, v55, s33
	v_add3_u32 v50, v50, v51, s33
	v_lshl_add_u64 v[48:49], v[48:49], 0, v[104:105]
	global_store_short_d16_hi v[52:53], v54, off offset:64
	global_store_short_d16_hi v[48:49], v50, off
	v_add_u32_e32 v48, s7, v128
	v_ashrrev_i32_e32 v49, 31, v48
	v_lshlrev_b64 v[48:49], 11, v[48:49]
	v_lshl_add_u64 v[48:49], s[44:45], 0, v[48:49]
	v_lshl_add_u64 v[110:111], v[48:49], 0, v[102:103]
	v_lshl_add_u64 v[108:109], v[48:49], 0, v[104:105]
	ds_read_b128 v[48:51], v78 offset:5184
	ds_read_b128 v[52:55], v78 offset:5440
	ds_read_b128 v[56:59], v78 offset:5696
	ds_read_b128 v[60:63], v78 offset:5952
	s_waitcnt lgkmcnt(2)
	v_pk_add_f32 v[48:49], v[48:49], v[52:53]
	s_waitcnt lgkmcnt(1)
	v_pk_add_f32 v[48:49], v[48:49], v[56:57]
	s_waitcnt lgkmcnt(0)
	v_pk_add_f32 v[48:49], v[48:49], v[60:61]
	s_nop 0
	v_pk_fma_f32 v[48:49], v[48:49], s[8:9], v[106:107] op_sel_hi:[1,0,0]
	s_nop 0
	v_mul_f32_e32 v52, 0x4b800000, v48
	v_cmp_gt_f32_e64 s[0:1], s2, v48
	v_cmp_gt_f32_e32 vcc, s2, v49
	s_nop 0
	v_cndmask_b32_e64 v48, v48, v52, s[0:1]
	v_rsq_f32_e32 v48, v48
	s_nop 0
	v_mul_f32_e32 v52, 0x45800000, v48
	v_cndmask_b32_e64 v48, v48, v52, s[0:1]
	v_mul_f32_e32 v44, v44, v48
	v_mul_f32_e32 v44, v186, v44
	v_bfe_u32 v52, v44, 16, 1
	v_mul_f32_e32 v40, v40, v48
	v_add3_u32 v44, v44, v52, s33
	v_mul_f32_e32 v40, v101, v40
	global_store_short_d16_hi v[110:111], v44, off
	v_bfe_u32 v44, v40, 16, 1
	v_mul_f32_e32 v36, v36, v48
	v_add3_u32 v40, v40, v44, s33
	v_mul_f32_e32 v36, v95, v36
	global_store_short_d16_hi v[110:111], v40, off offset:32
	v_bfe_u32 v40, v36, 16, 1
	v_mul_f32_e32 v32, v32, v48
	v_add3_u32 v36, v36, v40, s33
	v_mul_f32_e32 v32, v187, v32
	global_store_short_d16_hi v[110:111], v36, off offset:64
	v_bfe_u32 v36, v32, 16, 1
	v_add3_u32 v32, v32, v36, s33
	global_store_short_d16_hi v[108:109], v32, off
	v_mul_f32_e32 v32, 0x4b800000, v49
	v_cndmask_b32_e32 v32, v49, v32, vcc
	v_rsq_f32_e32 v32, v32
	v_add_u32_e32 v48, s7, v129
	v_ashrrev_i32_e32 v49, 31, v48
	v_lshlrev_b64 v[48:49], 11, v[48:49]
	v_mul_f32_e32 v36, 0x45800000, v32
	v_cndmask_b32_e32 v32, v32, v36, vcc
	v_mul_f32_e32 v36, v45, v32
	v_mul_f32_e32 v36, v186, v36
	v_lshl_add_u64 v[48:49], s[44:45], 0, v[48:49]
	v_bfe_u32 v40, v36, 16, 1
	v_add3_u32 v36, v36, v40, s33
	v_lshl_add_u64 v[44:45], v[48:49], 0, v[102:103]
	global_store_short_d16_hi v[44:45], v36, off
	v_mul_f32_e32 v36, v41, v32
	v_mul_f32_e32 v36, v101, v36
	v_bfe_u32 v40, v36, 16, 1
	v_add3_u32 v36, v36, v40, s33
	global_store_short_d16_hi v[44:45], v36, off offset:32
	v_mul_f32_e32 v36, v37, v32
	v_pk_add_f32 v[40:41], v[50:51], v[54:55]
	v_mul_f32_e32 v36, v95, v36
	v_pk_add_f32 v[40:41], v[40:41], v[58:59]
	v_bfe_u32 v37, v36, 16, 1
	v_pk_add_f32 v[40:41], v[40:41], v[62:63]
	v_add3_u32 v36, v36, v37, s33
	v_pk_fma_f32 v[40:41], v[40:41], s[8:9], v[106:107] op_sel_hi:[1,0,0]
	global_store_short_d16_hi v[44:45], v36, off offset:64
	v_mul_f32_e32 v44, 0x4b800000, v40
	v_cmp_gt_f32_e64 s[0:1], s2, v40
	v_mul_f32_e32 v32, v33, v32
	v_mul_f32_e32 v32, v187, v32
	v_cndmask_b32_e64 v40, v40, v44, s[0:1]
	v_rsq_f32_e32 v40, v40
	v_bfe_u32 v33, v32, 16, 1
	v_add3_u32 v36, v32, v33, s33
	v_lshl_add_u64 v[32:33], v[48:49], 0, v[104:105]
	v_mul_f32_e32 v44, 0x45800000, v40
	global_store_short_d16_hi v[32:33], v36, off
	v_add_u32_e32 v32, s7, v130
	v_cndmask_b32_e64 v40, v40, v44, s[0:1]
	v_ashrrev_i32_e32 v33, 31, v32
	v_mul_f32_e32 v44, v46, v40
	v_lshlrev_b64 v[32:33], 11, v[32:33]
	v_mul_f32_e32 v44, v186, v44
	v_lshl_add_u64 v[32:33], s[44:45], 0, v[32:33]
	v_bfe_u32 v45, v44, 16, 1
	v_mul_f32_e32 v42, v42, v40
	v_lshl_add_u64 v[36:37], v[32:33], 0, v[102:103]
	v_add3_u32 v44, v44, v45, s33
	v_mul_f32_e32 v42, v101, v42
	global_store_short_d16_hi v[36:37], v44, off
	v_bfe_u32 v44, v42, 16, 1
	v_mul_f32_e32 v38, v38, v40
	v_add3_u32 v42, v42, v44, s33
	v_mul_f32_e32 v38, v95, v38
	global_store_short_d16_hi v[36:37], v42, off offset:32
	v_bfe_u32 v42, v38, 16, 1
	v_mul_f32_e32 v34, v34, v40
	v_add3_u32 v38, v38, v42, s33
	v_mul_f32_e32 v34, v187, v34
	global_store_short_d16_hi v[36:37], v38, off offset:64
	v_bfe_u32 v36, v34, 16, 1
	v_lshl_add_u64 v[32:33], v[32:33], 0, v[104:105]
	v_add3_u32 v34, v34, v36, s33
	v_cmp_gt_f32_e32 vcc, s2, v41
	global_store_short_d16_hi v[32:33], v34, off
	v_mul_f32_e32 v32, 0x4b800000, v41
	v_cndmask_b32_e32 v32, v41, v32, vcc
	v_rsq_f32_e32 v32, v32
	s_nop 0
	v_mul_f32_e32 v33, 0x45800000, v32
	v_cndmask_b32_e32 v34, v32, v33, vcc
	v_add_u32_e32 v32, s7, v131
	v_ashrrev_i32_e32 v33, 31, v32
	v_mul_f32_e32 v36, v47, v34
	v_lshlrev_b64 v[32:33], 11, v[32:33]
	v_mul_f32_e32 v36, v186, v36
	v_lshl_add_u64 v[32:33], s[44:45], 0, v[32:33]
	v_bfe_u32 v37, v36, 16, 1
	v_add3_u32 v38, v36, v37, s33
	v_lshl_add_u64 v[36:37], v[32:33], 0, v[102:103]
	global_store_short_d16_hi v[36:37], v38, off
	v_mul_f32_e32 v38, v43, v34
	v_mul_f32_e32 v38, v101, v38
	v_bfe_u32 v40, v38, 16, 1
	v_add3_u32 v38, v38, v40, s33
	global_store_short_d16_hi v[36:37], v38, off offset:32
	v_mul_f32_e32 v38, v39, v34
	v_mul_f32_e32 v34, v35, v34
	v_mul_f32_e32 v38, v95, v38
	v_mul_f32_e32 v34, v187, v34
	v_bfe_u32 v39, v38, 16, 1
	v_bfe_u32 v35, v34, 16, 1
	v_add3_u32 v38, v38, v39, s33
	v_add3_u32 v34, v34, v35, s33
	v_lshl_add_u64 v[32:33], v[32:33], 0, v[104:105]
	v_cmp_gt_u32_e32 vcc, s92, v132
	global_store_short_d16_hi v[36:37], v38, off offset:64
	global_store_short_d16_hi v[32:33], v34, off
	s_and_saveexec_b64 s[0:1], vcc
	s_cbranch_execnz .LBB0_321
	s_or_b64 exec, exec, s[0:1]
	v_cmp_gt_u32_e32 vcc, s92, v133
	s_and_saveexec_b64 s[0:1], vcc
	s_cbranch_execnz .LBB0_322
